# act stores of the SwiGLU epilogue made write-through (sc0 sc1): less dirty L2 data to flush at the grid barrier
# baseline (speedup 1.0000x reference)
; __device__ __forceinline__ float rs_from(const float* p, int n4, float inv_n) {
;     float s = 0.f;
;     for (int i = 0; i < n4; ++i) { const f32x4 v = *(const f32x4*)(p + 4 * i); s += (v[0] + v[1]) + (v[2] + v[3]); }
;     return rsqrtf(s * inv_n + EPS);
;     __device__ __forceinline__ void operator()(AccRef acc, const pg8::Unit& u, int wr, int wc, int fr, int fq) const {
;         const int row0 = u.pm * 256 + wr * 64 + fr, col0 = u.pn * 128 + wc * 32 + 8 * fq;
; #pragma unroll
;         for (int ai = 0; ai < 2; ++ai)
; #pragma unroll
;             for (int m = 0; m < 4; ++m) {
;                 const int row = row0 + ai * 128 + m * 16;
;                 const float rs = rs_from(ssp + (size_t)row * 16, 4, 1.0f / 1024.0f);
;                 f32x4 o[2];
; #pragma unroll
;                 for (int n = 0; n < 2; ++n)
; #pragma unroll
;                     for (int j = 0; j < 4; ++j) {
;                         const float g = acc[ai][0][m][n][j] * rs, up = acc[ai][1][m][n][j] * rs;
;                         o[n][j] = g * __builtin_amdgcn_rcpf(1.0f + __expf(-g)) * up;
;                     }
;                 *(u32x4*)(act + (size_t)row * FF + col0) = pack8(o[0], o[1]);
.LBB0_376:
.Lswi_beg0:
	v_add_u32_e32 v249, 0x2000, v247
	global_load_dwordx4 v[154:157], v249, s[46:47]
	global_load_dwordx4 v[158:161], v249, s[46:47] offset:1024
	global_load_dwordx4 v[162:165], v249, s[46:47] offset:2048
	global_load_dwordx4 v[166:169], v249, s[46:47] offset:3072
	v_mbcnt_lo_u32_b32 v170, -1, 0
	v_mbcnt_hi_u32_b32 v170, -1, v170
	v_xor_b32_e32 v171, 16, v170
	v_xor_b32_e32 v172, 32, v170
	v_lshlrev_b32_e32 v171, 2, v171
	v_lshlrev_b32_e32 v172, 2, v172
	v_lshl_or_b32 v173, s61, 7, v148
	v_lshlrev_b32_e32 v173, 1, v173
	v_mad_u32_u24 v248, v246, s51, v173
	s_waitcnt vmcnt(12)
	v_add_f32_e32 v230, v230, v231
	v_add_f32_e32 v232, v232, v233
	v_add_f32_e32 v234, v234, v235
	v_add_f32_e32 v236, v236, v237
	v_add_f32_e32 v238, v238, v239
	v_add_f32_e32 v240, v240, v241
	v_add_f32_e32 v242, v242, v243
	v_add_f32_e32 v244, v244, v245
	v_add_f32_e32 v230, v230, v232
	v_add_f32_e32 v234, v234, v236
	v_add_f32_e32 v238, v238, v240
	v_add_f32_e32 v242, v242, v244
	ds_bpermute_b32 v231, v171, v230
	ds_bpermute_b32 v235, v171, v234
	ds_bpermute_b32 v239, v171, v238
	ds_bpermute_b32 v243, v171, v242
	s_waitcnt lgkmcnt(0)
	v_add_f32_e32 v230, v230, v231
	v_add_f32_e32 v234, v234, v235
	v_add_f32_e32 v238, v238, v239
	v_add_f32_e32 v242, v242, v243
	ds_bpermute_b32 v231, v172, v230
	ds_bpermute_b32 v235, v172, v234
	ds_bpermute_b32 v239, v172, v238
	ds_bpermute_b32 v243, v172, v242
	s_waitcnt lgkmcnt(0)
	v_add_f32_e32 v230, v230, v231
	v_add_f32_e32 v234, v234, v235
	v_add_f32_e32 v238, v238, v239
	v_add_f32_e32 v242, v242, v243
	v_fmamk_f32 v230, v230, 0x3a800000, v152
	v_fmamk_f32 v234, v234, 0x3a800000, v152
	v_fmamk_f32 v238, v238, 0x3a800000, v152
	v_fmamk_f32 v242, v242, 0x3a800000, v152
	v_rsq_f32_e32 v230, v230
	v_rsq_f32_e32 v234, v234
	v_rsq_f32_e32 v238, v238
	v_rsq_f32_e32 v242, v242
	s_nop 0
	v_pk_mul_f32 v[116:117], v[116:117], v[230:231] op_sel_hi:[1,0]
	v_pk_mul_f32 v[118:119], v[118:119], v[230:231] op_sel_hi:[1,0]
	v_pk_mul_f32 v[112:113], v[112:113], v[230:231] op_sel_hi:[1,0]
	v_pk_mul_f32 v[114:115], v[114:115], v[230:231] op_sel_hi:[1,0]
	v_pk_mul_f32 v[124:125], v[124:125], v[230:231] op_sel_hi:[1,0]
	v_pk_mul_f32 v[126:127], v[126:127], v[230:231] op_sel_hi:[1,0]
	v_pk_mul_f32 v[120:121], v[120:121], v[230:231] op_sel_hi:[1,0]
	v_pk_mul_f32 v[122:123], v[122:123], v[230:231] op_sel_hi:[1,0]
	v_mul_f32_e32 v176, 0xbfb8aa3b, v116
	v_mul_f32_e32 v177, 0xbfb8aa3b, v117
	v_mul_f32_e32 v178, 0xbfb8aa3b, v118
	v_mul_f32_e32 v179, 0xbfb8aa3b, v119
	v_mul_f32_e32 v180, 0xbfb8aa3b, v112
	v_mul_f32_e32 v181, 0xbfb8aa3b, v113
	v_mul_f32_e32 v182, 0xbfb8aa3b, v114
	v_mul_f32_e32 v183, 0xbfb8aa3b, v115
	v_exp_f32_e32 v176, v176
	v_exp_f32_e32 v177, v177
	v_exp_f32_e32 v178, v178
	v_exp_f32_e32 v179, v179
	v_exp_f32_e32 v180, v180
	v_exp_f32_e32 v181, v181
	v_exp_f32_e32 v182, v182
	v_exp_f32_e32 v183, v183
	v_add_f32_e32 v176, 1.0, v176
	v_add_f32_e32 v177, 1.0, v177
	v_add_f32_e32 v178, 1.0, v178
	v_add_f32_e32 v179, 1.0, v179
	v_add_f32_e32 v180, 1.0, v180
	v_add_f32_e32 v181, 1.0, v181
	v_add_f32_e32 v182, 1.0, v182
	v_add_f32_e32 v183, 1.0, v183
	v_rcp_f32_e32 v176, v176
	v_rcp_f32_e32 v177, v177
	v_rcp_f32_e32 v178, v178
	v_rcp_f32_e32 v179, v179
	v_rcp_f32_e32 v180, v180
	v_rcp_f32_e32 v181, v181
	v_rcp_f32_e32 v182, v182
	v_rcp_f32_e32 v183, v183
	v_mul_f32_e32 v176, v116, v176
	v_mul_f32_e32 v177, v117, v177
	v_mul_f32_e32 v178, v118, v178
	v_mul_f32_e32 v179, v119, v179
	v_mul_f32_e32 v180, v112, v180
	v_mul_f32_e32 v181, v113, v181
	v_mul_f32_e32 v182, v114, v182
	v_mul_f32_e32 v183, v115, v183
	v_mul_f32_e32 v176, v124, v176
	v_mul_f32_e32 v177, v125, v177
	v_mul_f32_e32 v178, v126, v178
	v_mul_f32_e32 v179, v127, v179
	v_mul_f32_e32 v180, v120, v180
	v_mul_f32_e32 v181, v121, v181
	v_mul_f32_e32 v182, v122, v182
	v_mul_f32_e32 v183, v123, v183
	v_cvt_pk_bf16_f32 v192, v176, v177
	v_cvt_pk_bf16_f32 v193, v178, v179
	v_cvt_pk_bf16_f32 v194, v180, v181
	v_cvt_pk_bf16_f32 v195, v182, v183
	v_mov_b32_e32 v200, v248
	global_store_dwordx4 v200, v[192:195], s[48:49] sc0 sc1
	v_pk_mul_f32 v[100:101], v[100:101], v[234:235] op_sel_hi:[1,0]
	v_pk_mul_f32 v[102:103], v[102:103], v[234:235] op_sel_hi:[1,0]
	v_pk_mul_f32 v[96:97], v[96:97], v[234:235] op_sel_hi:[1,0]
	v_pk_mul_f32 v[98:99], v[98:99], v[234:235] op_sel_hi:[1,0]
	v_pk_mul_f32 v[108:109], v[108:109], v[234:235] op_sel_hi:[1,0]
	v_pk_mul_f32 v[110:111], v[110:111], v[234:235] op_sel_hi:[1,0]
	v_pk_mul_f32 v[104:105], v[104:105], v[234:235] op_sel_hi:[1,0]
	v_pk_mul_f32 v[106:107], v[106:107], v[234:235] op_sel_hi:[1,0]
	v_mul_f32_e32 v184, 0xbfb8aa3b, v100
	v_mul_f32_e32 v185, 0xbfb8aa3b, v101
	v_mul_f32_e32 v186, 0xbfb8aa3b, v102
	v_mul_f32_e32 v187, 0xbfb8aa3b, v103
	v_mul_f32_e32 v188, 0xbfb8aa3b, v96
	v_mul_f32_e32 v189, 0xbfb8aa3b, v97
	v_mul_f32_e32 v190, 0xbfb8aa3b, v98
	v_mul_f32_e32 v191, 0xbfb8aa3b, v99
	v_exp_f32_e32 v184, v184
	v_exp_f32_e32 v185, v185
	v_exp_f32_e32 v186, v186
	v_exp_f32_e32 v187, v187
	v_exp_f32_e32 v188, v188
	v_exp_f32_e32 v189, v189
	v_exp_f32_e32 v190, v190
	v_exp_f32_e32 v191, v191
	v_add_f32_e32 v184, 1.0, v184
	v_add_f32_e32 v185, 1.0, v185
	v_add_f32_e32 v186, 1.0, v186
	v_add_f32_e32 v187, 1.0, v187
	v_add_f32_e32 v188, 1.0, v188
	v_add_f32_e32 v189, 1.0, v189
	v_add_f32_e32 v190, 1.0, v190
	v_add_f32_e32 v191, 1.0, v191
	v_rcp_f32_e32 v184, v184
	v_rcp_f32_e32 v185, v185
	v_rcp_f32_e32 v186, v186
	v_rcp_f32_e32 v187, v187
	v_rcp_f32_e32 v188, v188
	v_rcp_f32_e32 v189, v189
	v_rcp_f32_e32 v190, v190
	v_rcp_f32_e32 v191, v191
	v_mul_f32_e32 v184, v100, v184
	v_mul_f32_e32 v185, v101, v185
	v_mul_f32_e32 v186, v102, v186
; __device__ __forceinline__ float rs_from(const float* p, int n4, float inv_n) {
;     float s = 0.f;
;     for (int i = 0; i < n4; ++i) { const f32x4 v = *(const f32x4*)(p + 4 * i); s += (v[0] + v[1]) + (v[2] + v[3]); }
;     return rsqrtf(s * inv_n + EPS);
;     __device__ __forceinline__ void operator()(AccRef acc, const pg8::Unit& u, int wr, int wc, int fr, int fq) const {
;     ...
;             for (int m = 0; m < 4; ++m) {
;                 const int row = row0 + ai * 128 + m * 16;
;                 const float rs = rs_from(ssp + (size_t)row * 16, 4, 1.0f / 1024.0f);
;                 f32x4 o[2];
; #pragma unroll
;                 for (int n = 0; n < 2; ++n)
; #pragma unroll
;                     for (int j = 0; j < 4; ++j) {
;                         const float g = acc[ai][0][m][n][j] * rs, up = acc[ai][1][m][n][j] * rs;
;                         o[n][j] = g * __builtin_amdgcn_rcpf(1.0f + __expf(-g)) * up;
;                     }
;                 *(u32x4*)(act + (size_t)row * FF + col0) = pack8(o[0], o[1]);
	v_mul_f32_e32 v187, v103, v187
	v_mul_f32_e32 v188, v96, v188
	v_mul_f32_e32 v189, v97, v189
	v_mul_f32_e32 v190, v98, v190
	v_mul_f32_e32 v191, v99, v191
	v_mul_f32_e32 v184, v108, v184
	v_mul_f32_e32 v185, v109, v185
	v_mul_f32_e32 v186, v110, v186
	v_mul_f32_e32 v187, v111, v187
	v_mul_f32_e32 v188, v104, v188
	v_mul_f32_e32 v189, v105, v189
	v_mul_f32_e32 v190, v106, v190
	v_mul_f32_e32 v191, v107, v191
	v_cvt_pk_bf16_f32 v196, v184, v185
	v_cvt_pk_bf16_f32 v197, v186, v187
	v_cvt_pk_bf16_f32 v198, v188, v189
	v_cvt_pk_bf16_f32 v199, v190, v191
	v_add_u32_e32 v201, 0x16000, v248
	global_store_dwordx4 v201, v[196:199], s[48:49] sc0 sc1
	v_pk_mul_f32 v[84:85], v[84:85], v[238:239] op_sel_hi:[1,0]
	v_pk_mul_f32 v[86:87], v[86:87], v[238:239] op_sel_hi:[1,0]
	v_pk_mul_f32 v[80:81], v[80:81], v[238:239] op_sel_hi:[1,0]
	v_pk_mul_f32 v[82:83], v[82:83], v[238:239] op_sel_hi:[1,0]
	v_pk_mul_f32 v[92:93], v[92:93], v[238:239] op_sel_hi:[1,0]
	v_pk_mul_f32 v[94:95], v[94:95], v[238:239] op_sel_hi:[1,0]
	v_pk_mul_f32 v[88:89], v[88:89], v[238:239] op_sel_hi:[1,0]
	v_pk_mul_f32 v[90:91], v[90:91], v[238:239] op_sel_hi:[1,0]
	v_mul_f32_e32 v176, 0xbfb8aa3b, v84
	v_mul_f32_e32 v177, 0xbfb8aa3b, v85
	v_mul_f32_e32 v178, 0xbfb8aa3b, v86
	v_mul_f32_e32 v179, 0xbfb8aa3b, v87
	v_mul_f32_e32 v180, 0xbfb8aa3b, v80
	v_mul_f32_e32 v181, 0xbfb8aa3b, v81
	v_mul_f32_e32 v182, 0xbfb8aa3b, v82
	v_mul_f32_e32 v183, 0xbfb8aa3b, v83
	v_exp_f32_e32 v176, v176
	v_exp_f32_e32 v177, v177
	v_exp_f32_e32 v178, v178
	v_exp_f32_e32 v179, v179
	v_exp_f32_e32 v180, v180
	v_exp_f32_e32 v181, v181
	v_exp_f32_e32 v182, v182
	v_exp_f32_e32 v183, v183
	v_add_f32_e32 v176, 1.0, v176
	v_add_f32_e32 v177, 1.0, v177
	v_add_f32_e32 v178, 1.0, v178
	v_add_f32_e32 v179, 1.0, v179
	v_add_f32_e32 v180, 1.0, v180
	v_add_f32_e32 v181, 1.0, v181
	v_add_f32_e32 v182, 1.0, v182
	v_add_f32_e32 v183, 1.0, v183
	v_rcp_f32_e32 v176, v176
	v_rcp_f32_e32 v177, v177
	v_rcp_f32_e32 v178, v178
	v_rcp_f32_e32 v179, v179
	v_rcp_f32_e32 v180, v180
	v_rcp_f32_e32 v181, v181
	v_rcp_f32_e32 v182, v182
	v_rcp_f32_e32 v183, v183
	v_mul_f32_e32 v176, v84, v176
	v_mul_f32_e32 v177, v85, v177
	v_mul_f32_e32 v178, v86, v178
	v_mul_f32_e32 v179, v87, v179
	v_mul_f32_e32 v180, v80, v180
	v_mul_f32_e32 v181, v81, v181
	v_mul_f32_e32 v182, v82, v182
	v_mul_f32_e32 v183, v83, v183
	v_mul_f32_e32 v176, v92, v176
	v_mul_f32_e32 v177, v93, v177
	v_mul_f32_e32 v178, v94, v178
	v_mul_f32_e32 v179, v95, v179
	v_mul_f32_e32 v180, v88, v180
	v_mul_f32_e32 v181, v89, v181
	v_mul_f32_e32 v182, v90, v182
	v_mul_f32_e32 v183, v91, v183
	v_cvt_pk_bf16_f32 v192, v176, v177
	v_cvt_pk_bf16_f32 v193, v178, v179
	v_cvt_pk_bf16_f32 v194, v180, v181
	v_cvt_pk_bf16_f32 v195, v182, v183
	v_add_u32_e32 v200, 0x2c000, v248
	global_store_dwordx4 v200, v[192:195], s[48:49] sc0 sc1
	v_pk_mul_f32 v[68:69], v[68:69], v[242:243] op_sel_hi:[1,0]
	v_pk_mul_f32 v[70:71], v[70:71], v[242:243] op_sel_hi:[1,0]
	v_pk_mul_f32 v[64:65], v[64:65], v[242:243] op_sel_hi:[1,0]
	v_pk_mul_f32 v[66:67], v[66:67], v[242:243] op_sel_hi:[1,0]
	v_pk_mul_f32 v[76:77], v[76:77], v[242:243] op_sel_hi:[1,0]
	v_pk_mul_f32 v[78:79], v[78:79], v[242:243] op_sel_hi:[1,0]
	v_pk_mul_f32 v[72:73], v[72:73], v[242:243] op_sel_hi:[1,0]
	v_pk_mul_f32 v[74:75], v[74:75], v[242:243] op_sel_hi:[1,0]
	v_mul_f32_e32 v184, 0xbfb8aa3b, v68
	v_mul_f32_e32 v185, 0xbfb8aa3b, v69
	v_mul_f32_e32 v186, 0xbfb8aa3b, v70
	v_mul_f32_e32 v187, 0xbfb8aa3b, v71
	v_mul_f32_e32 v188, 0xbfb8aa3b, v64
	v_mul_f32_e32 v189, 0xbfb8aa3b, v65
	v_mul_f32_e32 v190, 0xbfb8aa3b, v66
	v_mul_f32_e32 v191, 0xbfb8aa3b, v67
	v_exp_f32_e32 v184, v184
	v_exp_f32_e32 v185, v185
	v_exp_f32_e32 v186, v186
	v_exp_f32_e32 v187, v187
	v_exp_f32_e32 v188, v188
	v_exp_f32_e32 v189, v189
	v_exp_f32_e32 v190, v190
	v_exp_f32_e32 v191, v191
	v_add_f32_e32 v184, 1.0, v184
	v_add_f32_e32 v185, 1.0, v185
	v_add_f32_e32 v186, 1.0, v186
	v_add_f32_e32 v187, 1.0, v187
	v_add_f32_e32 v188, 1.0, v188
	v_add_f32_e32 v189, 1.0, v189
	v_add_f32_e32 v190, 1.0, v190
	v_add_f32_e32 v191, 1.0, v191
	v_rcp_f32_e32 v184, v184
	v_rcp_f32_e32 v185, v185
	v_rcp_f32_e32 v186, v186
	v_rcp_f32_e32 v187, v187
	v_rcp_f32_e32 v188, v188
	v_rcp_f32_e32 v189, v189
	v_rcp_f32_e32 v190, v190
	v_rcp_f32_e32 v191, v191
	v_mul_f32_e32 v184, v68, v184
	v_mul_f32_e32 v185, v69, v185
	v_mul_f32_e32 v186, v70, v186
	v_mul_f32_e32 v187, v71, v187
	v_mul_f32_e32 v188, v64, v188
	v_mul_f32_e32 v189, v65, v189
	v_mul_f32_e32 v190, v66, v190
	v_mul_f32_e32 v191, v67, v191
	v_mul_f32_e32 v184, v76, v184
	v_mul_f32_e32 v185, v77, v185
	v_mul_f32_e32 v186, v78, v186
	v_mul_f32_e32 v187, v79, v187
	v_mul_f32_e32 v188, v72, v188
	v_mul_f32_e32 v189, v73, v189
	v_mul_f32_e32 v190, v74, v190
	v_mul_f32_e32 v191, v75, v191
	v_cvt_pk_bf16_f32 v196, v184, v185
	v_cvt_pk_bf16_f32 v197, v186, v187
	v_cvt_pk_bf16_f32 v198, v188, v189
	v_cvt_pk_bf16_f32 v199, v190, v191
	v_add_u32_e32 v201, 0x42000, v248
	global_store_dwordx4 v201, v[196:199], s[48:49] sc0 sc1
	s_waitcnt vmcnt(4)
	v_add_f32_e32 v154, v154, v155
	v_add_f32_e32 v156, v156, v157
	v_add_f32_e32 v158, v158, v159
	v_add_f32_e32 v160, v160, v161
	v_add_f32_e32 v162, v162, v163
	v_add_f32_e32 v164, v164, v165
	v_add_f32_e32 v166, v166, v167
	v_add_f32_e32 v168, v168, v169
	v_add_f32_e32 v154, v154, v156
	v_add_f32_e32 v158, v158, v160
	v_add_f32_e32 v162, v162, v164
	v_add_f32_e32 v166, v166, v168
	ds_bpermute_b32 v155, v171, v154
	ds_bpermute_b32 v159, v171, v158
	ds_bpermute_b32 v163, v171, v162
	ds_bpermute_b32 v167, v171, v166
	s_waitcnt lgkmcnt(0)
; __device__ __forceinline__ float rs_from(const float* p, int n4, float inv_n) {
;     float s = 0.f;
;     for (int i = 0; i < n4; ++i) { const f32x4 v = *(const f32x4*)(p + 4 * i); s += (v[0] + v[1]) + (v[2] + v[3]); }
;     return rsqrtf(s * inv_n + EPS);
;     __device__ __forceinline__ void operator()(AccRef acc, const pg8::Unit& u, int wr, int wc, int fr, int fq) const {
;     ...
;             for (int m = 0; m < 4; ++m) {
;                 const int row = row0 + ai * 128 + m * 16;
;                 const float rs = rs_from(ssp + (size_t)row * 16, 4, 1.0f / 1024.0f);
;                 f32x4 o[2];
; #pragma unroll
;                 for (int n = 0; n < 2; ++n)
; #pragma unroll
;                     for (int j = 0; j < 4; ++j) {
;                         const float g = acc[ai][0][m][n][j] * rs, up = acc[ai][1][m][n][j] * rs;
;                         o[n][j] = g * __builtin_amdgcn_rcpf(1.0f + __expf(-g)) * up;
;                     }
;                 *(u32x4*)(act + (size_t)row * FF + col0) = pack8(o[0], o[1]);
	v_add_f32_e32 v154, v154, v155
	v_add_f32_e32 v158, v158, v159
	v_add_f32_e32 v162, v162, v163
	v_add_f32_e32 v166, v166, v167
	ds_bpermute_b32 v155, v172, v154
	ds_bpermute_b32 v159, v172, v158
	ds_bpermute_b32 v163, v172, v162
	ds_bpermute_b32 v167, v172, v166
	s_waitcnt lgkmcnt(0)
	v_add_f32_e32 v154, v154, v155
	v_add_f32_e32 v158, v158, v159
	v_add_f32_e32 v162, v162, v163
	v_add_f32_e32 v166, v166, v167
	v_fmamk_f32 v154, v154, 0x3a800000, v152
	v_fmamk_f32 v158, v158, 0x3a800000, v152
	v_fmamk_f32 v162, v162, 0x3a800000, v152
	v_fmamk_f32 v166, v166, 0x3a800000, v152
	v_rsq_f32_e32 v154, v154
	v_rsq_f32_e32 v158, v158
	v_rsq_f32_e32 v162, v162
	v_rsq_f32_e32 v166, v166
	s_nop 0
	v_pk_mul_f32 v[52:53], v[52:53], v[154:155] op_sel_hi:[1,0]
	v_pk_mul_f32 v[54:55], v[54:55], v[154:155] op_sel_hi:[1,0]
	v_pk_mul_f32 v[48:49], v[48:49], v[154:155] op_sel_hi:[1,0]
	v_pk_mul_f32 v[50:51], v[50:51], v[154:155] op_sel_hi:[1,0]
	v_pk_mul_f32 v[60:61], v[60:61], v[154:155] op_sel_hi:[1,0]
	v_pk_mul_f32 v[62:63], v[62:63], v[154:155] op_sel_hi:[1,0]
	v_pk_mul_f32 v[56:57], v[56:57], v[154:155] op_sel_hi:[1,0]
	v_pk_mul_f32 v[58:59], v[58:59], v[154:155] op_sel_hi:[1,0]
	v_mul_f32_e32 v176, 0xbfb8aa3b, v52
	v_mul_f32_e32 v177, 0xbfb8aa3b, v53
	v_mul_f32_e32 v178, 0xbfb8aa3b, v54
	v_mul_f32_e32 v179, 0xbfb8aa3b, v55
	v_mul_f32_e32 v180, 0xbfb8aa3b, v48
	v_mul_f32_e32 v181, 0xbfb8aa3b, v49
	v_mul_f32_e32 v182, 0xbfb8aa3b, v50
	v_mul_f32_e32 v183, 0xbfb8aa3b, v51
	v_exp_f32_e32 v176, v176
	v_exp_f32_e32 v177, v177
	v_exp_f32_e32 v178, v178
	v_exp_f32_e32 v179, v179
	v_exp_f32_e32 v180, v180
	v_exp_f32_e32 v181, v181
	v_exp_f32_e32 v182, v182
	v_exp_f32_e32 v183, v183
	v_add_f32_e32 v176, 1.0, v176
	v_add_f32_e32 v177, 1.0, v177
	v_add_f32_e32 v178, 1.0, v178
	v_add_f32_e32 v179, 1.0, v179
	v_add_f32_e32 v180, 1.0, v180
	v_add_f32_e32 v181, 1.0, v181
	v_add_f32_e32 v182, 1.0, v182
	v_add_f32_e32 v183, 1.0, v183
	v_rcp_f32_e32 v176, v176
	v_rcp_f32_e32 v177, v177
	v_rcp_f32_e32 v178, v178
	v_rcp_f32_e32 v179, v179
	v_rcp_f32_e32 v180, v180
	v_rcp_f32_e32 v181, v181
	v_rcp_f32_e32 v182, v182
	v_rcp_f32_e32 v183, v183
	v_mul_f32_e32 v176, v52, v176
	v_mul_f32_e32 v177, v53, v177
	v_mul_f32_e32 v178, v54, v178
	v_mul_f32_e32 v179, v55, v179
	v_mul_f32_e32 v180, v48, v180
	v_mul_f32_e32 v181, v49, v181
	v_mul_f32_e32 v182, v50, v182
	v_mul_f32_e32 v183, v51, v183
	v_mul_f32_e32 v176, v60, v176
	v_mul_f32_e32 v177, v61, v177
	v_mul_f32_e32 v178, v62, v178
	v_mul_f32_e32 v179, v63, v179
	v_mul_f32_e32 v180, v56, v180
	v_mul_f32_e32 v181, v57, v181
	v_mul_f32_e32 v182, v58, v182
	v_mul_f32_e32 v183, v59, v183
	v_cvt_pk_bf16_f32 v192, v176, v177
	v_cvt_pk_bf16_f32 v193, v178, v179
	v_cvt_pk_bf16_f32 v194, v180, v181
	v_cvt_pk_bf16_f32 v195, v182, v183
	v_add_u32_e32 v200, 0xb0000, v248
	global_store_dwordx4 v200, v[192:195], s[48:49] sc0 sc1
	v_pk_mul_f32 v[36:37], v[36:37], v[158:159] op_sel_hi:[1,0]
	v_pk_mul_f32 v[38:39], v[38:39], v[158:159] op_sel_hi:[1,0]
	v_pk_mul_f32 v[32:33], v[32:33], v[158:159] op_sel_hi:[1,0]
	v_pk_mul_f32 v[34:35], v[34:35], v[158:159] op_sel_hi:[1,0]
	v_pk_mul_f32 v[44:45], v[44:45], v[158:159] op_sel_hi:[1,0]
	v_pk_mul_f32 v[46:47], v[46:47], v[158:159] op_sel_hi:[1,0]
	v_pk_mul_f32 v[40:41], v[40:41], v[158:159] op_sel_hi:[1,0]
	v_pk_mul_f32 v[42:43], v[42:43], v[158:159] op_sel_hi:[1,0]
	v_mul_f32_e32 v184, 0xbfb8aa3b, v36
	v_mul_f32_e32 v185, 0xbfb8aa3b, v37
	v_mul_f32_e32 v186, 0xbfb8aa3b, v38
	v_mul_f32_e32 v187, 0xbfb8aa3b, v39
	v_mul_f32_e32 v188, 0xbfb8aa3b, v32
	v_mul_f32_e32 v189, 0xbfb8aa3b, v33
	v_mul_f32_e32 v190, 0xbfb8aa3b, v34
	v_mul_f32_e32 v191, 0xbfb8aa3b, v35
	v_exp_f32_e32 v184, v184
	v_exp_f32_e32 v185, v185
	v_exp_f32_e32 v186, v186
	v_exp_f32_e32 v187, v187
	v_exp_f32_e32 v188, v188
	v_exp_f32_e32 v189, v189
	v_exp_f32_e32 v190, v190
	v_exp_f32_e32 v191, v191
	v_add_f32_e32 v184, 1.0, v184
	v_add_f32_e32 v185, 1.0, v185
	v_add_f32_e32 v186, 1.0, v186
	v_add_f32_e32 v187, 1.0, v187
	v_add_f32_e32 v188, 1.0, v188
	v_add_f32_e32 v189, 1.0, v189
	v_add_f32_e32 v190, 1.0, v190
	v_add_f32_e32 v191, 1.0, v191
	v_rcp_f32_e32 v184, v184
	v_rcp_f32_e32 v185, v185
	v_rcp_f32_e32 v186, v186
	v_rcp_f32_e32 v187, v187
	v_rcp_f32_e32 v188, v188
	v_rcp_f32_e32 v189, v189
	v_rcp_f32_e32 v190, v190
	v_rcp_f32_e32 v191, v191
	v_mul_f32_e32 v184, v36, v184
	v_mul_f32_e32 v185, v37, v185
	v_mul_f32_e32 v186, v38, v186
	v_mul_f32_e32 v187, v39, v187
	v_mul_f32_e32 v188, v32, v188
	v_mul_f32_e32 v189, v33, v189
	v_mul_f32_e32 v190, v34, v190
	v_mul_f32_e32 v191, v35, v191
	v_mul_f32_e32 v184, v44, v184
	v_mul_f32_e32 v185, v45, v185
	v_mul_f32_e32 v186, v46, v186
	v_mul_f32_e32 v187, v47, v187
;     __device__ __forceinline__ void operator()(AccRef acc, const pg8::Unit& u, int wr, int wc, int fr, int fq) const {
;     ...
;             for (int m = 0; m < 4; ++m) {
;                 const int row = row0 + ai * 128 + m * 16;
;                 const float rs = rs_from(ssp + (size_t)row * 16, 4, 1.0f / 1024.0f);
;                 f32x4 o[2];
; #pragma unroll
;                 for (int n = 0; n < 2; ++n)
; #pragma unroll
;                     for (int j = 0; j < 4; ++j) {
;                         const float g = acc[ai][0][m][n][j] * rs, up = acc[ai][1][m][n][j] * rs;
;                         o[n][j] = g * __builtin_amdgcn_rcpf(1.0f + __expf(-g)) * up;
;                     }
;                 *(u32x4*)(act + (size_t)row * FF + col0) = pack8(o[0], o[1]);
	v_mul_f32_e32 v188, v40, v188
	v_mul_f32_e32 v189, v41, v189
	v_mul_f32_e32 v190, v42, v190
	v_mul_f32_e32 v191, v43, v191
	v_cvt_pk_bf16_f32 v196, v184, v185
	v_cvt_pk_bf16_f32 v197, v186, v187
	v_cvt_pk_bf16_f32 v198, v188, v189
	v_cvt_pk_bf16_f32 v199, v190, v191
	v_add_u32_e32 v201, 0xc6000, v248
	global_store_dwordx4 v201, v[196:199], s[48:49] sc0 sc1
	v_pk_mul_f32 v[20:21], v[20:21], v[162:163] op_sel_hi:[1,0]
	v_pk_mul_f32 v[22:23], v[22:23], v[162:163] op_sel_hi:[1,0]
	v_pk_mul_f32 v[16:17], v[16:17], v[162:163] op_sel_hi:[1,0]
	v_pk_mul_f32 v[18:19], v[18:19], v[162:163] op_sel_hi:[1,0]
	v_pk_mul_f32 v[28:29], v[28:29], v[162:163] op_sel_hi:[1,0]
	v_pk_mul_f32 v[30:31], v[30:31], v[162:163] op_sel_hi:[1,0]
	v_pk_mul_f32 v[24:25], v[24:25], v[162:163] op_sel_hi:[1,0]
	v_pk_mul_f32 v[26:27], v[26:27], v[162:163] op_sel_hi:[1,0]
	v_mul_f32_e32 v176, 0xbfb8aa3b, v20
	v_mul_f32_e32 v177, 0xbfb8aa3b, v21
	v_mul_f32_e32 v178, 0xbfb8aa3b, v22
	v_mul_f32_e32 v179, 0xbfb8aa3b, v23
	v_mul_f32_e32 v180, 0xbfb8aa3b, v16
	v_mul_f32_e32 v181, 0xbfb8aa3b, v17
	v_mul_f32_e32 v182, 0xbfb8aa3b, v18
	v_mul_f32_e32 v183, 0xbfb8aa3b, v19
	v_exp_f32_e32 v176, v176
	v_exp_f32_e32 v177, v177
	v_exp_f32_e32 v178, v178
	v_exp_f32_e32 v179, v179
	v_exp_f32_e32 v180, v180
	v_exp_f32_e32 v181, v181
	v_exp_f32_e32 v182, v182
	v_exp_f32_e32 v183, v183
	v_add_f32_e32 v176, 1.0, v176
	v_add_f32_e32 v177, 1.0, v177
	v_add_f32_e32 v178, 1.0, v178
	v_add_f32_e32 v179, 1.0, v179
	v_add_f32_e32 v180, 1.0, v180
	v_add_f32_e32 v181, 1.0, v181
	v_add_f32_e32 v182, 1.0, v182
	v_add_f32_e32 v183, 1.0, v183
	v_rcp_f32_e32 v176, v176
	v_rcp_f32_e32 v177, v177
	v_rcp_f32_e32 v178, v178
	v_rcp_f32_e32 v179, v179
	v_rcp_f32_e32 v180, v180
	v_rcp_f32_e32 v181, v181
	v_rcp_f32_e32 v182, v182
	v_rcp_f32_e32 v183, v183
	v_mul_f32_e32 v176, v20, v176
	v_mul_f32_e32 v177, v21, v177
	v_mul_f32_e32 v178, v22, v178
	v_mul_f32_e32 v179, v23, v179
	v_mul_f32_e32 v180, v16, v180
	v_mul_f32_e32 v181, v17, v181
	v_mul_f32_e32 v182, v18, v182
	v_mul_f32_e32 v183, v19, v183
	v_mul_f32_e32 v176, v28, v176
	v_mul_f32_e32 v177, v29, v177
	v_mul_f32_e32 v178, v30, v178
	v_mul_f32_e32 v179, v31, v179
	v_mul_f32_e32 v180, v24, v180
	v_mul_f32_e32 v181, v25, v181
	v_mul_f32_e32 v182, v26, v182
	v_mul_f32_e32 v183, v27, v183
	v_cvt_pk_bf16_f32 v192, v176, v177
	v_cvt_pk_bf16_f32 v193, v178, v179
	v_cvt_pk_bf16_f32 v194, v180, v181
	v_cvt_pk_bf16_f32 v195, v182, v183
	v_add_u32_e32 v200, 0xdc000, v248
	global_store_dwordx4 v200, v[192:195], s[48:49] sc0 sc1
	v_pk_mul_f32 v[4:5], v[4:5], v[166:167] op_sel_hi:[1,0]
	v_pk_mul_f32 v[6:7], v[6:7], v[166:167] op_sel_hi:[1,0]
	v_pk_mul_f32 v[0:1], v[0:1], v[166:167] op_sel_hi:[1,0]
	v_pk_mul_f32 v[2:3], v[2:3], v[166:167] op_sel_hi:[1,0]
	v_pk_mul_f32 v[12:13], v[12:13], v[166:167] op_sel_hi:[1,0]
	v_pk_mul_f32 v[14:15], v[14:15], v[166:167] op_sel_hi:[1,0]
	v_pk_mul_f32 v[8:9], v[8:9], v[166:167] op_sel_hi:[1,0]
	v_pk_mul_f32 v[10:11], v[10:11], v[166:167] op_sel_hi:[1,0]
	v_mul_f32_e32 v184, 0xbfb8aa3b, v4
	v_mul_f32_e32 v185, 0xbfb8aa3b, v5
	v_mul_f32_e32 v186, 0xbfb8aa3b, v6
	v_mul_f32_e32 v187, 0xbfb8aa3b, v7
	v_mul_f32_e32 v188, 0xbfb8aa3b, v0
	v_mul_f32_e32 v189, 0xbfb8aa3b, v1
	v_mul_f32_e32 v190, 0xbfb8aa3b, v2
	v_mul_f32_e32 v191, 0xbfb8aa3b, v3
	v_exp_f32_e32 v184, v184
	v_exp_f32_e32 v185, v185
	v_exp_f32_e32 v186, v186
	v_exp_f32_e32 v187, v187
	v_exp_f32_e32 v188, v188
	v_exp_f32_e32 v189, v189
	v_exp_f32_e32 v190, v190
	v_exp_f32_e32 v191, v191
	v_add_f32_e32 v184, 1.0, v184
	v_add_f32_e32 v185, 1.0, v185
	v_add_f32_e32 v186, 1.0, v186
	v_add_f32_e32 v187, 1.0, v187
	v_add_f32_e32 v188, 1.0, v188
	v_add_f32_e32 v189, 1.0, v189
	v_add_f32_e32 v190, 1.0, v190
	v_add_f32_e32 v191, 1.0, v191
	v_rcp_f32_e32 v184, v184
	v_rcp_f32_e32 v185, v185
	v_rcp_f32_e32 v186, v186
	v_rcp_f32_e32 v187, v187
	v_rcp_f32_e32 v188, v188
	v_rcp_f32_e32 v189, v189
	v_rcp_f32_e32 v190, v190
	v_rcp_f32_e32 v191, v191
	v_mul_f32_e32 v184, v4, v184
	v_mul_f32_e32 v185, v5, v185
	v_mul_f32_e32 v186, v6, v186
	v_mul_f32_e32 v187, v7, v187
	v_mul_f32_e32 v188, v0, v188
	v_mul_f32_e32 v189, v1, v189
	v_mul_f32_e32 v190, v2, v190
	v_mul_f32_e32 v191, v3, v191
	v_mul_f32_e32 v184, v12, v184
	v_mul_f32_e32 v185, v13, v185
	v_mul_f32_e32 v186, v14, v186
	v_mul_f32_e32 v187, v15, v187
	v_mul_f32_e32 v188, v8, v188
	v_mul_f32_e32 v189, v9, v189
	v_mul_f32_e32 v190, v10, v190
	v_mul_f32_e32 v191, v11, v191
	v_cvt_pk_bf16_f32 v196, v184, v185
	v_cvt_pk_bf16_f32 v197, v186, v187
	v_cvt_pk_bf16_f32 v198, v188, v189
	v_cvt_pk_bf16_f32 v199, v190, v191
	v_add_u32_e32 v201, 0xf2000, v248
	global_store_dwordx4 v201, v[196:199], s[48:49] sc0 sc1

; __device__ __forceinline__ float rs_from(const float* p, int n4, float inv_n) {
;     float s = 0.f;
;     for (int i = 0; i < n4; ++i) { const f32x4 v = *(const f32x4*)(p + 4 * i); s += (v[0] + v[1]) + (v[2] + v[3]); }
;     return rsqrtf(s * inv_n + EPS);
;     __device__ __forceinline__ void operator()(AccRef acc, const pg8::Unit& u, int wr, int wc, int fr, int fq) const {
;         const int row0 = u.pm * 256 + wr * 64 + fr, col0 = u.pn * 128 + wc * 32 + 8 * fq;
; #pragma unroll
;         for (int ai = 0; ai < 2; ++ai)
; #pragma unroll
;             for (int m = 0; m < 4; ++m) {
;                 const int row = row0 + ai * 128 + m * 16;
;                 const float rs = rs_from(ssp + (size_t)row * 16, 4, 1.0f / 1024.0f);
;                 f32x4 o[2];
; #pragma unroll
;                 for (int n = 0; n < 2; ++n)
; #pragma unroll
;                     for (int j = 0; j < 4; ++j) {
;                         const float g = acc[ai][0][m][n][j] * rs, up = acc[ai][1][m][n][j] * rs;
;                         o[n][j] = g * __builtin_amdgcn_rcpf(1.0f + __expf(-g)) * up;
;                     }
;                 *(u32x4*)(act + (size_t)row * FF + col0) = pack8(o[0], o[1]);
.LBB0_1320:
.Lswi_beg1:
	v_add_u32_e32 v249, 0x2000, v247
	global_load_dwordx4 v[154:157], v249, s[46:47]
	global_load_dwordx4 v[158:161], v249, s[46:47] offset:1024
	global_load_dwordx4 v[162:165], v249, s[46:47] offset:2048
	global_load_dwordx4 v[166:169], v249, s[46:47] offset:3072
	v_mbcnt_lo_u32_b32 v170, -1, 0
	v_mbcnt_hi_u32_b32 v170, -1, v170
	v_xor_b32_e32 v171, 16, v170
	v_xor_b32_e32 v172, 32, v170
	v_lshlrev_b32_e32 v171, 2, v171
	v_lshlrev_b32_e32 v172, 2, v172
	v_lshl_or_b32 v173, s61, 7, v148
	v_lshlrev_b32_e32 v173, 1, v173
	v_mad_u32_u24 v248, v246, s57, v173
	s_waitcnt vmcnt(12)
	v_add_f32_e32 v230, v230, v231
	v_add_f32_e32 v232, v232, v233
	v_add_f32_e32 v234, v234, v235
	v_add_f32_e32 v236, v236, v237
	v_add_f32_e32 v238, v238, v239
	v_add_f32_e32 v240, v240, v241
	v_add_f32_e32 v242, v242, v243
	v_add_f32_e32 v244, v244, v245
	v_add_f32_e32 v230, v230, v232
	v_add_f32_e32 v234, v234, v236
	v_add_f32_e32 v238, v238, v240
	v_add_f32_e32 v242, v242, v244
	ds_bpermute_b32 v231, v171, v230
	ds_bpermute_b32 v235, v171, v234
	ds_bpermute_b32 v239, v171, v238
	ds_bpermute_b32 v243, v171, v242
	s_waitcnt lgkmcnt(0)
	v_add_f32_e32 v230, v230, v231
	v_add_f32_e32 v234, v234, v235
	v_add_f32_e32 v238, v238, v239
	v_add_f32_e32 v242, v242, v243
	ds_bpermute_b32 v231, v172, v230
	ds_bpermute_b32 v235, v172, v234
	ds_bpermute_b32 v239, v172, v238
	ds_bpermute_b32 v243, v172, v242
	s_waitcnt lgkmcnt(0)
	v_add_f32_e32 v230, v230, v231
	v_add_f32_e32 v234, v234, v235
	v_add_f32_e32 v238, v238, v239
	v_add_f32_e32 v242, v242, v243
	v_fmamk_f32 v230, v230, 0x3a800000, v152
	v_fmamk_f32 v234, v234, 0x3a800000, v152
	v_fmamk_f32 v238, v238, 0x3a800000, v152
	v_fmamk_f32 v242, v242, 0x3a800000, v152
	v_rsq_f32_e32 v230, v230
	v_rsq_f32_e32 v234, v234
	v_rsq_f32_e32 v238, v238
	v_rsq_f32_e32 v242, v242
	s_nop 0
	v_pk_mul_f32 v[116:117], v[116:117], v[230:231] op_sel_hi:[1,0]
	v_pk_mul_f32 v[118:119], v[118:119], v[230:231] op_sel_hi:[1,0]
	v_pk_mul_f32 v[112:113], v[112:113], v[230:231] op_sel_hi:[1,0]
	v_pk_mul_f32 v[114:115], v[114:115], v[230:231] op_sel_hi:[1,0]
	v_pk_mul_f32 v[124:125], v[124:125], v[230:231] op_sel_hi:[1,0]
	v_pk_mul_f32 v[126:127], v[126:127], v[230:231] op_sel_hi:[1,0]
	v_pk_mul_f32 v[120:121], v[120:121], v[230:231] op_sel_hi:[1,0]
	v_pk_mul_f32 v[122:123], v[122:123], v[230:231] op_sel_hi:[1,0]
	v_mul_f32_e32 v176, 0xbfb8aa3b, v116
	v_mul_f32_e32 v177, 0xbfb8aa3b, v117
	v_mul_f32_e32 v178, 0xbfb8aa3b, v118
	v_mul_f32_e32 v179, 0xbfb8aa3b, v119
	v_mul_f32_e32 v180, 0xbfb8aa3b, v112
	v_mul_f32_e32 v181, 0xbfb8aa3b, v113
	v_mul_f32_e32 v182, 0xbfb8aa3b, v114
	v_mul_f32_e32 v183, 0xbfb8aa3b, v115
	v_exp_f32_e32 v176, v176
	v_exp_f32_e32 v177, v177
	v_exp_f32_e32 v178, v178
	v_exp_f32_e32 v179, v179
	v_exp_f32_e32 v180, v180
	v_exp_f32_e32 v181, v181
	v_exp_f32_e32 v182, v182
	v_exp_f32_e32 v183, v183
	v_add_f32_e32 v176, 1.0, v176
	v_add_f32_e32 v177, 1.0, v177
	v_add_f32_e32 v178, 1.0, v178
	v_add_f32_e32 v179, 1.0, v179
	v_add_f32_e32 v180, 1.0, v180
	v_add_f32_e32 v181, 1.0, v181
	v_add_f32_e32 v182, 1.0, v182
	v_add_f32_e32 v183, 1.0, v183
	v_rcp_f32_e32 v176, v176
	v_rcp_f32_e32 v177, v177
	v_rcp_f32_e32 v178, v178
	v_rcp_f32_e32 v179, v179
	v_rcp_f32_e32 v180, v180
	v_rcp_f32_e32 v181, v181
	v_rcp_f32_e32 v182, v182
	v_rcp_f32_e32 v183, v183
	v_mul_f32_e32 v176, v116, v176
	v_mul_f32_e32 v177, v117, v177
	v_mul_f32_e32 v178, v118, v178
	v_mul_f32_e32 v179, v119, v179
	v_mul_f32_e32 v180, v112, v180
	v_mul_f32_e32 v181, v113, v181
	v_mul_f32_e32 v182, v114, v182
	v_mul_f32_e32 v183, v115, v183
	v_mul_f32_e32 v176, v124, v176
	v_mul_f32_e32 v177, v125, v177
	v_mul_f32_e32 v178, v126, v178
	v_mul_f32_e32 v179, v127, v179
	v_mul_f32_e32 v180, v120, v180
	v_mul_f32_e32 v181, v121, v181
	v_mul_f32_e32 v182, v122, v182
	v_mul_f32_e32 v183, v123, v183
	v_cvt_pk_bf16_f32 v192, v176, v177
	v_cvt_pk_bf16_f32 v193, v178, v179
	v_cvt_pk_bf16_f32 v194, v180, v181
	v_cvt_pk_bf16_f32 v195, v182, v183
	v_mov_b32_e32 v200, v248
	global_store_dwordx4 v200, v[192:195], s[48:49] sc0 sc1
	v_pk_mul_f32 v[100:101], v[100:101], v[234:235] op_sel_hi:[1,0]
	v_pk_mul_f32 v[102:103], v[102:103], v[234:235] op_sel_hi:[1,0]
	v_pk_mul_f32 v[96:97], v[96:97], v[234:235] op_sel_hi:[1,0]
	v_pk_mul_f32 v[98:99], v[98:99], v[234:235] op_sel_hi:[1,0]
	v_pk_mul_f32 v[108:109], v[108:109], v[234:235] op_sel_hi:[1,0]
	v_pk_mul_f32 v[110:111], v[110:111], v[234:235] op_sel_hi:[1,0]
	v_pk_mul_f32 v[104:105], v[104:105], v[234:235] op_sel_hi:[1,0]
	v_pk_mul_f32 v[106:107], v[106:107], v[234:235] op_sel_hi:[1,0]
	v_mul_f32_e32 v184, 0xbfb8aa3b, v100
	v_mul_f32_e32 v185, 0xbfb8aa3b, v101
	v_mul_f32_e32 v186, 0xbfb8aa3b, v102
	v_mul_f32_e32 v187, 0xbfb8aa3b, v103
	v_mul_f32_e32 v188, 0xbfb8aa3b, v96
	v_mul_f32_e32 v189, 0xbfb8aa3b, v97
	v_mul_f32_e32 v190, 0xbfb8aa3b, v98
	v_mul_f32_e32 v191, 0xbfb8aa3b, v99
	v_exp_f32_e32 v184, v184
	v_exp_f32_e32 v185, v185
	v_exp_f32_e32 v186, v186
	v_exp_f32_e32 v187, v187
	v_exp_f32_e32 v188, v188
	v_exp_f32_e32 v189, v189
	v_exp_f32_e32 v190, v190
	v_exp_f32_e32 v191, v191
	v_add_f32_e32 v184, 1.0, v184
	v_add_f32_e32 v185, 1.0, v185
	v_add_f32_e32 v186, 1.0, v186
	v_add_f32_e32 v187, 1.0, v187
	v_add_f32_e32 v188, 1.0, v188
	v_add_f32_e32 v189, 1.0, v189
	v_add_f32_e32 v190, 1.0, v190
	v_add_f32_e32 v191, 1.0, v191
	v_rcp_f32_e32 v184, v184
	v_rcp_f32_e32 v185, v185
	v_rcp_f32_e32 v186, v186
	v_rcp_f32_e32 v187, v187
	v_rcp_f32_e32 v188, v188
	v_rcp_f32_e32 v189, v189
	v_rcp_f32_e32 v190, v190
	v_rcp_f32_e32 v191, v191
	v_mul_f32_e32 v184, v100, v184
	v_mul_f32_e32 v185, v101, v185
	v_mul_f32_e32 v186, v102, v186
; __device__ __forceinline__ float rs_from(const float* p, int n4, float inv_n) {
;     float s = 0.f;
;     for (int i = 0; i < n4; ++i) { const f32x4 v = *(const f32x4*)(p + 4 * i); s += (v[0] + v[1]) + (v[2] + v[3]); }
;     return rsqrtf(s * inv_n + EPS);
;     __device__ __forceinline__ void operator()(AccRef acc, const pg8::Unit& u, int wr, int wc, int fr, int fq) const {
;     ...
;             for (int m = 0; m < 4; ++m) {
;                 const int row = row0 + ai * 128 + m * 16;
;                 const float rs = rs_from(ssp + (size_t)row * 16, 4, 1.0f / 1024.0f);
;                 f32x4 o[2];
; #pragma unroll
;                 for (int n = 0; n < 2; ++n)
; #pragma unroll
;                     for (int j = 0; j < 4; ++j) {
;                         const float g = acc[ai][0][m][n][j] * rs, up = acc[ai][1][m][n][j] * rs;
;                         o[n][j] = g * __builtin_amdgcn_rcpf(1.0f + __expf(-g)) * up;
;                     }
;                 *(u32x4*)(act + (size_t)row * FF + col0) = pack8(o[0], o[1]);
	v_mul_f32_e32 v187, v103, v187
	v_mul_f32_e32 v188, v96, v188
	v_mul_f32_e32 v189, v97, v189
	v_mul_f32_e32 v190, v98, v190
	v_mul_f32_e32 v191, v99, v191
	v_mul_f32_e32 v184, v108, v184
	v_mul_f32_e32 v185, v109, v185
	v_mul_f32_e32 v186, v110, v186
	v_mul_f32_e32 v187, v111, v187
	v_mul_f32_e32 v188, v104, v188
	v_mul_f32_e32 v189, v105, v189
	v_mul_f32_e32 v190, v106, v190
	v_mul_f32_e32 v191, v107, v191
	v_cvt_pk_bf16_f32 v196, v184, v185
	v_cvt_pk_bf16_f32 v197, v186, v187
	v_cvt_pk_bf16_f32 v198, v188, v189
	v_cvt_pk_bf16_f32 v199, v190, v191
	v_add_u32_e32 v201, 0x16000, v248
	global_store_dwordx4 v201, v[196:199], s[48:49] sc0 sc1
	v_pk_mul_f32 v[84:85], v[84:85], v[238:239] op_sel_hi:[1,0]
	v_pk_mul_f32 v[86:87], v[86:87], v[238:239] op_sel_hi:[1,0]
	v_pk_mul_f32 v[80:81], v[80:81], v[238:239] op_sel_hi:[1,0]
	v_pk_mul_f32 v[82:83], v[82:83], v[238:239] op_sel_hi:[1,0]
	v_pk_mul_f32 v[92:93], v[92:93], v[238:239] op_sel_hi:[1,0]
	v_pk_mul_f32 v[94:95], v[94:95], v[238:239] op_sel_hi:[1,0]
	v_pk_mul_f32 v[88:89], v[88:89], v[238:239] op_sel_hi:[1,0]
	v_pk_mul_f32 v[90:91], v[90:91], v[238:239] op_sel_hi:[1,0]
	v_mul_f32_e32 v176, 0xbfb8aa3b, v84
	v_mul_f32_e32 v177, 0xbfb8aa3b, v85
	v_mul_f32_e32 v178, 0xbfb8aa3b, v86
	v_mul_f32_e32 v179, 0xbfb8aa3b, v87
	v_mul_f32_e32 v180, 0xbfb8aa3b, v80
	v_mul_f32_e32 v181, 0xbfb8aa3b, v81
	v_mul_f32_e32 v182, 0xbfb8aa3b, v82
	v_mul_f32_e32 v183, 0xbfb8aa3b, v83
	v_exp_f32_e32 v176, v176
	v_exp_f32_e32 v177, v177
	v_exp_f32_e32 v178, v178
	v_exp_f32_e32 v179, v179
	v_exp_f32_e32 v180, v180
	v_exp_f32_e32 v181, v181
	v_exp_f32_e32 v182, v182
	v_exp_f32_e32 v183, v183
	v_add_f32_e32 v176, 1.0, v176
	v_add_f32_e32 v177, 1.0, v177
	v_add_f32_e32 v178, 1.0, v178
	v_add_f32_e32 v179, 1.0, v179
	v_add_f32_e32 v180, 1.0, v180
	v_add_f32_e32 v181, 1.0, v181
	v_add_f32_e32 v182, 1.0, v182
	v_add_f32_e32 v183, 1.0, v183
	v_rcp_f32_e32 v176, v176
	v_rcp_f32_e32 v177, v177
	v_rcp_f32_e32 v178, v178
	v_rcp_f32_e32 v179, v179
	v_rcp_f32_e32 v180, v180
	v_rcp_f32_e32 v181, v181
	v_rcp_f32_e32 v182, v182
	v_rcp_f32_e32 v183, v183
	v_mul_f32_e32 v176, v84, v176
	v_mul_f32_e32 v177, v85, v177
	v_mul_f32_e32 v178, v86, v178
	v_mul_f32_e32 v179, v87, v179
	v_mul_f32_e32 v180, v80, v180
	v_mul_f32_e32 v181, v81, v181
	v_mul_f32_e32 v182, v82, v182
	v_mul_f32_e32 v183, v83, v183
	v_mul_f32_e32 v176, v92, v176
	v_mul_f32_e32 v177, v93, v177
	v_mul_f32_e32 v178, v94, v178
	v_mul_f32_e32 v179, v95, v179
	v_mul_f32_e32 v180, v88, v180
	v_mul_f32_e32 v181, v89, v181
	v_mul_f32_e32 v182, v90, v182
	v_mul_f32_e32 v183, v91, v183
	v_cvt_pk_bf16_f32 v192, v176, v177
	v_cvt_pk_bf16_f32 v193, v178, v179
	v_cvt_pk_bf16_f32 v194, v180, v181
	v_cvt_pk_bf16_f32 v195, v182, v183
	v_add_u32_e32 v200, 0x2c000, v248
	global_store_dwordx4 v200, v[192:195], s[48:49] sc0 sc1
	v_pk_mul_f32 v[68:69], v[68:69], v[242:243] op_sel_hi:[1,0]
	v_pk_mul_f32 v[70:71], v[70:71], v[242:243] op_sel_hi:[1,0]
	v_pk_mul_f32 v[64:65], v[64:65], v[242:243] op_sel_hi:[1,0]
	v_pk_mul_f32 v[66:67], v[66:67], v[242:243] op_sel_hi:[1,0]
	v_pk_mul_f32 v[76:77], v[76:77], v[242:243] op_sel_hi:[1,0]
	v_pk_mul_f32 v[78:79], v[78:79], v[242:243] op_sel_hi:[1,0]
	v_pk_mul_f32 v[72:73], v[72:73], v[242:243] op_sel_hi:[1,0]
	v_pk_mul_f32 v[74:75], v[74:75], v[242:243] op_sel_hi:[1,0]
	v_mul_f32_e32 v184, 0xbfb8aa3b, v68
	v_mul_f32_e32 v185, 0xbfb8aa3b, v69
	v_mul_f32_e32 v186, 0xbfb8aa3b, v70
	v_mul_f32_e32 v187, 0xbfb8aa3b, v71
	v_mul_f32_e32 v188, 0xbfb8aa3b, v64
	v_mul_f32_e32 v189, 0xbfb8aa3b, v65
	v_mul_f32_e32 v190, 0xbfb8aa3b, v66
	v_mul_f32_e32 v191, 0xbfb8aa3b, v67
	v_exp_f32_e32 v184, v184
	v_exp_f32_e32 v185, v185
	v_exp_f32_e32 v186, v186
	v_exp_f32_e32 v187, v187
	v_exp_f32_e32 v188, v188
	v_exp_f32_e32 v189, v189
	v_exp_f32_e32 v190, v190
	v_exp_f32_e32 v191, v191
	v_add_f32_e32 v184, 1.0, v184
	v_add_f32_e32 v185, 1.0, v185
	v_add_f32_e32 v186, 1.0, v186
	v_add_f32_e32 v187, 1.0, v187
	v_add_f32_e32 v188, 1.0, v188
	v_add_f32_e32 v189, 1.0, v189
	v_add_f32_e32 v190, 1.0, v190
	v_add_f32_e32 v191, 1.0, v191
	v_rcp_f32_e32 v184, v184
	v_rcp_f32_e32 v185, v185
	v_rcp_f32_e32 v186, v186
	v_rcp_f32_e32 v187, v187
	v_rcp_f32_e32 v188, v188
	v_rcp_f32_e32 v189, v189
	v_rcp_f32_e32 v190, v190
	v_rcp_f32_e32 v191, v191
	v_mul_f32_e32 v184, v68, v184
	v_mul_f32_e32 v185, v69, v185
	v_mul_f32_e32 v186, v70, v186
	v_mul_f32_e32 v187, v71, v187
	v_mul_f32_e32 v188, v64, v188
	v_mul_f32_e32 v189, v65, v189
	v_mul_f32_e32 v190, v66, v190
	v_mul_f32_e32 v191, v67, v191
	v_mul_f32_e32 v184, v76, v184
	v_mul_f32_e32 v185, v77, v185
	v_mul_f32_e32 v186, v78, v186
	v_mul_f32_e32 v187, v79, v187
	v_mul_f32_e32 v188, v72, v188
	v_mul_f32_e32 v189, v73, v189
	v_mul_f32_e32 v190, v74, v190
	v_mul_f32_e32 v191, v75, v191
	v_cvt_pk_bf16_f32 v196, v184, v185
	v_cvt_pk_bf16_f32 v197, v186, v187
	v_cvt_pk_bf16_f32 v198, v188, v189
	v_cvt_pk_bf16_f32 v199, v190, v191
	v_add_u32_e32 v201, 0x42000, v248
	global_store_dwordx4 v201, v[196:199], s[48:49] sc0 sc1
	s_waitcnt vmcnt(4)
	v_add_f32_e32 v154, v154, v155
	v_add_f32_e32 v156, v156, v157
	v_add_f32_e32 v158, v158, v159
	v_add_f32_e32 v160, v160, v161
	v_add_f32_e32 v162, v162, v163
	v_add_f32_e32 v164, v164, v165
	v_add_f32_e32 v166, v166, v167
	v_add_f32_e32 v168, v168, v169
	v_add_f32_e32 v154, v154, v156
	v_add_f32_e32 v158, v158, v160
	v_add_f32_e32 v162, v162, v164
	v_add_f32_e32 v166, v166, v168
	ds_bpermute_b32 v155, v171, v154
	ds_bpermute_b32 v159, v171, v158
	ds_bpermute_b32 v163, v171, v162
	ds_bpermute_b32 v167, v171, v166
	s_waitcnt lgkmcnt(0)
; __device__ __forceinline__ float rs_from(const float* p, int n4, float inv_n) {
;     float s = 0.f;
;     for (int i = 0; i < n4; ++i) { const f32x4 v = *(const f32x4*)(p + 4 * i); s += (v[0] + v[1]) + (v[2] + v[3]); }
;     return rsqrtf(s * inv_n + EPS);
;     __device__ __forceinline__ void operator()(AccRef acc, const pg8::Unit& u, int wr, int wc, int fr, int fq) const {
;     ...
;             for (int m = 0; m < 4; ++m) {
;                 const int row = row0 + ai * 128 + m * 16;
;                 const float rs = rs_from(ssp + (size_t)row * 16, 4, 1.0f / 1024.0f);
;                 f32x4 o[2];
; #pragma unroll
;                 for (int n = 0; n < 2; ++n)
; #pragma unroll
;                     for (int j = 0; j < 4; ++j) {
;                         const float g = acc[ai][0][m][n][j] * rs, up = acc[ai][1][m][n][j] * rs;
;                         o[n][j] = g * __builtin_amdgcn_rcpf(1.0f + __expf(-g)) * up;
;                     }
;                 *(u32x4*)(act + (size_t)row * FF + col0) = pack8(o[0], o[1]);
	v_add_f32_e32 v154, v154, v155
	v_add_f32_e32 v158, v158, v159
	v_add_f32_e32 v162, v162, v163
	v_add_f32_e32 v166, v166, v167
	ds_bpermute_b32 v155, v172, v154
	ds_bpermute_b32 v159, v172, v158
	ds_bpermute_b32 v163, v172, v162
	ds_bpermute_b32 v167, v172, v166
	s_waitcnt lgkmcnt(0)
	v_add_f32_e32 v154, v154, v155
	v_add_f32_e32 v158, v158, v159
	v_add_f32_e32 v162, v162, v163
	v_add_f32_e32 v166, v166, v167
	v_fmamk_f32 v154, v154, 0x3a800000, v152
	v_fmamk_f32 v158, v158, 0x3a800000, v152
	v_fmamk_f32 v162, v162, 0x3a800000, v152
	v_fmamk_f32 v166, v166, 0x3a800000, v152
	v_rsq_f32_e32 v154, v154
	v_rsq_f32_e32 v158, v158
	v_rsq_f32_e32 v162, v162
	v_rsq_f32_e32 v166, v166
	s_nop 0
	v_pk_mul_f32 v[52:53], v[52:53], v[154:155] op_sel_hi:[1,0]
	v_pk_mul_f32 v[54:55], v[54:55], v[154:155] op_sel_hi:[1,0]
	v_pk_mul_f32 v[48:49], v[48:49], v[154:155] op_sel_hi:[1,0]
	v_pk_mul_f32 v[50:51], v[50:51], v[154:155] op_sel_hi:[1,0]
	v_pk_mul_f32 v[60:61], v[60:61], v[154:155] op_sel_hi:[1,0]
	v_pk_mul_f32 v[62:63], v[62:63], v[154:155] op_sel_hi:[1,0]
	v_pk_mul_f32 v[56:57], v[56:57], v[154:155] op_sel_hi:[1,0]
	v_pk_mul_f32 v[58:59], v[58:59], v[154:155] op_sel_hi:[1,0]
	v_mul_f32_e32 v176, 0xbfb8aa3b, v52
	v_mul_f32_e32 v177, 0xbfb8aa3b, v53
	v_mul_f32_e32 v178, 0xbfb8aa3b, v54
	v_mul_f32_e32 v179, 0xbfb8aa3b, v55
	v_mul_f32_e32 v180, 0xbfb8aa3b, v48
	v_mul_f32_e32 v181, 0xbfb8aa3b, v49
	v_mul_f32_e32 v182, 0xbfb8aa3b, v50
	v_mul_f32_e32 v183, 0xbfb8aa3b, v51
	v_exp_f32_e32 v176, v176
	v_exp_f32_e32 v177, v177
	v_exp_f32_e32 v178, v178
	v_exp_f32_e32 v179, v179
	v_exp_f32_e32 v180, v180
	v_exp_f32_e32 v181, v181
	v_exp_f32_e32 v182, v182
	v_exp_f32_e32 v183, v183
	v_add_f32_e32 v176, 1.0, v176
	v_add_f32_e32 v177, 1.0, v177
	v_add_f32_e32 v178, 1.0, v178
	v_add_f32_e32 v179, 1.0, v179
	v_add_f32_e32 v180, 1.0, v180
	v_add_f32_e32 v181, 1.0, v181
	v_add_f32_e32 v182, 1.0, v182
	v_add_f32_e32 v183, 1.0, v183
	v_rcp_f32_e32 v176, v176
	v_rcp_f32_e32 v177, v177
	v_rcp_f32_e32 v178, v178
	v_rcp_f32_e32 v179, v179
	v_rcp_f32_e32 v180, v180
	v_rcp_f32_e32 v181, v181
	v_rcp_f32_e32 v182, v182
	v_rcp_f32_e32 v183, v183
	v_mul_f32_e32 v176, v52, v176
	v_mul_f32_e32 v177, v53, v177
	v_mul_f32_e32 v178, v54, v178
	v_mul_f32_e32 v179, v55, v179
	v_mul_f32_e32 v180, v48, v180
	v_mul_f32_e32 v181, v49, v181
	v_mul_f32_e32 v182, v50, v182
	v_mul_f32_e32 v183, v51, v183
	v_mul_f32_e32 v176, v60, v176
	v_mul_f32_e32 v177, v61, v177
	v_mul_f32_e32 v178, v62, v178
	v_mul_f32_e32 v179, v63, v179
	v_mul_f32_e32 v180, v56, v180
	v_mul_f32_e32 v181, v57, v181
	v_mul_f32_e32 v182, v58, v182
	v_mul_f32_e32 v183, v59, v183
	v_cvt_pk_bf16_f32 v192, v176, v177
	v_cvt_pk_bf16_f32 v193, v178, v179
	v_cvt_pk_bf16_f32 v194, v180, v181
	v_cvt_pk_bf16_f32 v195, v182, v183
	v_add_u32_e32 v200, 0xb0000, v248
	global_store_dwordx4 v200, v[192:195], s[48:49] sc0 sc1
	v_pk_mul_f32 v[36:37], v[36:37], v[158:159] op_sel_hi:[1,0]
	v_pk_mul_f32 v[38:39], v[38:39], v[158:159] op_sel_hi:[1,0]
	v_pk_mul_f32 v[32:33], v[32:33], v[158:159] op_sel_hi:[1,0]
	v_pk_mul_f32 v[34:35], v[34:35], v[158:159] op_sel_hi:[1,0]
	v_pk_mul_f32 v[44:45], v[44:45], v[158:159] op_sel_hi:[1,0]
	v_pk_mul_f32 v[46:47], v[46:47], v[158:159] op_sel_hi:[1,0]
	v_pk_mul_f32 v[40:41], v[40:41], v[158:159] op_sel_hi:[1,0]
	v_pk_mul_f32 v[42:43], v[42:43], v[158:159] op_sel_hi:[1,0]
	v_mul_f32_e32 v184, 0xbfb8aa3b, v36
	v_mul_f32_e32 v185, 0xbfb8aa3b, v37
	v_mul_f32_e32 v186, 0xbfb8aa3b, v38
	v_mul_f32_e32 v187, 0xbfb8aa3b, v39
	v_mul_f32_e32 v188, 0xbfb8aa3b, v32
	v_mul_f32_e32 v189, 0xbfb8aa3b, v33
	v_mul_f32_e32 v190, 0xbfb8aa3b, v34
	v_mul_f32_e32 v191, 0xbfb8aa3b, v35
	v_exp_f32_e32 v184, v184
	v_exp_f32_e32 v185, v185
	v_exp_f32_e32 v186, v186
	v_exp_f32_e32 v187, v187
	v_exp_f32_e32 v188, v188
	v_exp_f32_e32 v189, v189
	v_exp_f32_e32 v190, v190
	v_exp_f32_e32 v191, v191
	v_add_f32_e32 v184, 1.0, v184
	v_add_f32_e32 v185, 1.0, v185
	v_add_f32_e32 v186, 1.0, v186
	v_add_f32_e32 v187, 1.0, v187
	v_add_f32_e32 v188, 1.0, v188
	v_add_f32_e32 v189, 1.0, v189
	v_add_f32_e32 v190, 1.0, v190
	v_add_f32_e32 v191, 1.0, v191
	v_rcp_f32_e32 v184, v184
	v_rcp_f32_e32 v185, v185
	v_rcp_f32_e32 v186, v186
	v_rcp_f32_e32 v187, v187
	v_rcp_f32_e32 v188, v188
	v_rcp_f32_e32 v189, v189
	v_rcp_f32_e32 v190, v190
	v_rcp_f32_e32 v191, v191
	v_mul_f32_e32 v184, v36, v184
	v_mul_f32_e32 v185, v37, v185
	v_mul_f32_e32 v186, v38, v186
	v_mul_f32_e32 v187, v39, v187
	v_mul_f32_e32 v188, v32, v188
	v_mul_f32_e32 v189, v33, v189
	v_mul_f32_e32 v190, v34, v190
	v_mul_f32_e32 v191, v35, v191
	v_mul_f32_e32 v184, v44, v184
	v_mul_f32_e32 v185, v45, v185
	v_mul_f32_e32 v186, v46, v186
	v_mul_f32_e32 v187, v47, v187
;     __device__ __forceinline__ void operator()(AccRef acc, const pg8::Unit& u, int wr, int wc, int fr, int fq) const {
;     ...
;             for (int m = 0; m < 4; ++m) {
;                 const int row = row0 + ai * 128 + m * 16;
;                 const float rs = rs_from(ssp + (size_t)row * 16, 4, 1.0f / 1024.0f);
;                 f32x4 o[2];
; #pragma unroll
;                 for (int n = 0; n < 2; ++n)
; #pragma unroll
;                     for (int j = 0; j < 4; ++j) {
;                         const float g = acc[ai][0][m][n][j] * rs, up = acc[ai][1][m][n][j] * rs;
;                         o[n][j] = g * __builtin_amdgcn_rcpf(1.0f + __expf(-g)) * up;
;                     }
;                 *(u32x4*)(act + (size_t)row * FF + col0) = pack8(o[0], o[1]);
	v_mul_f32_e32 v188, v40, v188
	v_mul_f32_e32 v189, v41, v189
	v_mul_f32_e32 v190, v42, v190
	v_mul_f32_e32 v191, v43, v191
	v_cvt_pk_bf16_f32 v196, v184, v185
	v_cvt_pk_bf16_f32 v197, v186, v187
	v_cvt_pk_bf16_f32 v198, v188, v189
	v_cvt_pk_bf16_f32 v199, v190, v191
	v_add_u32_e32 v201, 0xc6000, v248
	global_store_dwordx4 v201, v[196:199], s[48:49] sc0 sc1
	v_pk_mul_f32 v[20:21], v[20:21], v[162:163] op_sel_hi:[1,0]
	v_pk_mul_f32 v[22:23], v[22:23], v[162:163] op_sel_hi:[1,0]
	v_pk_mul_f32 v[16:17], v[16:17], v[162:163] op_sel_hi:[1,0]
	v_pk_mul_f32 v[18:19], v[18:19], v[162:163] op_sel_hi:[1,0]
	v_pk_mul_f32 v[28:29], v[28:29], v[162:163] op_sel_hi:[1,0]
	v_pk_mul_f32 v[30:31], v[30:31], v[162:163] op_sel_hi:[1,0]
	v_pk_mul_f32 v[24:25], v[24:25], v[162:163] op_sel_hi:[1,0]
	v_pk_mul_f32 v[26:27], v[26:27], v[162:163] op_sel_hi:[1,0]
	v_mul_f32_e32 v176, 0xbfb8aa3b, v20
	v_mul_f32_e32 v177, 0xbfb8aa3b, v21
	v_mul_f32_e32 v178, 0xbfb8aa3b, v22
	v_mul_f32_e32 v179, 0xbfb8aa3b, v23
	v_mul_f32_e32 v180, 0xbfb8aa3b, v16
	v_mul_f32_e32 v181, 0xbfb8aa3b, v17
	v_mul_f32_e32 v182, 0xbfb8aa3b, v18
	v_mul_f32_e32 v183, 0xbfb8aa3b, v19
	v_exp_f32_e32 v176, v176
	v_exp_f32_e32 v177, v177
	v_exp_f32_e32 v178, v178
	v_exp_f32_e32 v179, v179
	v_exp_f32_e32 v180, v180
	v_exp_f32_e32 v181, v181
	v_exp_f32_e32 v182, v182
	v_exp_f32_e32 v183, v183
	v_add_f32_e32 v176, 1.0, v176
	v_add_f32_e32 v177, 1.0, v177
	v_add_f32_e32 v178, 1.0, v178
	v_add_f32_e32 v179, 1.0, v179
	v_add_f32_e32 v180, 1.0, v180
	v_add_f32_e32 v181, 1.0, v181
	v_add_f32_e32 v182, 1.0, v182
	v_add_f32_e32 v183, 1.0, v183
	v_rcp_f32_e32 v176, v176
	v_rcp_f32_e32 v177, v177
	v_rcp_f32_e32 v178, v178
	v_rcp_f32_e32 v179, v179
	v_rcp_f32_e32 v180, v180
	v_rcp_f32_e32 v181, v181
	v_rcp_f32_e32 v182, v182
	v_rcp_f32_e32 v183, v183
	v_mul_f32_e32 v176, v20, v176
	v_mul_f32_e32 v177, v21, v177
	v_mul_f32_e32 v178, v22, v178
	v_mul_f32_e32 v179, v23, v179
	v_mul_f32_e32 v180, v16, v180
	v_mul_f32_e32 v181, v17, v181
	v_mul_f32_e32 v182, v18, v182
	v_mul_f32_e32 v183, v19, v183
	v_mul_f32_e32 v176, v28, v176
	v_mul_f32_e32 v177, v29, v177
	v_mul_f32_e32 v178, v30, v178
	v_mul_f32_e32 v179, v31, v179
	v_mul_f32_e32 v180, v24, v180
	v_mul_f32_e32 v181, v25, v181
	v_mul_f32_e32 v182, v26, v182
	v_mul_f32_e32 v183, v27, v183
	v_cvt_pk_bf16_f32 v192, v176, v177
	v_cvt_pk_bf16_f32 v193, v178, v179
	v_cvt_pk_bf16_f32 v194, v180, v181
	v_cvt_pk_bf16_f32 v195, v182, v183
	v_add_u32_e32 v200, 0xdc000, v248
	global_store_dwordx4 v200, v[192:195], s[48:49] sc0 sc1
	v_pk_mul_f32 v[4:5], v[4:5], v[166:167] op_sel_hi:[1,0]
	v_pk_mul_f32 v[6:7], v[6:7], v[166:167] op_sel_hi:[1,0]
	v_pk_mul_f32 v[0:1], v[0:1], v[166:167] op_sel_hi:[1,0]
	v_pk_mul_f32 v[2:3], v[2:3], v[166:167] op_sel_hi:[1,0]
	v_pk_mul_f32 v[12:13], v[12:13], v[166:167] op_sel_hi:[1,0]
	v_pk_mul_f32 v[14:15], v[14:15], v[166:167] op_sel_hi:[1,0]
	v_pk_mul_f32 v[8:9], v[8:9], v[166:167] op_sel_hi:[1,0]
	v_pk_mul_f32 v[10:11], v[10:11], v[166:167] op_sel_hi:[1,0]
	v_mul_f32_e32 v184, 0xbfb8aa3b, v4
	v_mul_f32_e32 v185, 0xbfb8aa3b, v5
	v_mul_f32_e32 v186, 0xbfb8aa3b, v6
	v_mul_f32_e32 v187, 0xbfb8aa3b, v7
	v_mul_f32_e32 v188, 0xbfb8aa3b, v0
	v_mul_f32_e32 v189, 0xbfb8aa3b, v1
	v_mul_f32_e32 v190, 0xbfb8aa3b, v2
	v_mul_f32_e32 v191, 0xbfb8aa3b, v3
	v_exp_f32_e32 v184, v184
	v_exp_f32_e32 v185, v185
	v_exp_f32_e32 v186, v186
	v_exp_f32_e32 v187, v187
	v_exp_f32_e32 v188, v188
	v_exp_f32_e32 v189, v189
	v_exp_f32_e32 v190, v190
	v_exp_f32_e32 v191, v191
	v_add_f32_e32 v184, 1.0, v184
	v_add_f32_e32 v185, 1.0, v185
	v_add_f32_e32 v186, 1.0, v186
	v_add_f32_e32 v187, 1.0, v187
	v_add_f32_e32 v188, 1.0, v188
	v_add_f32_e32 v189, 1.0, v189
	v_add_f32_e32 v190, 1.0, v190
	v_add_f32_e32 v191, 1.0, v191
	v_rcp_f32_e32 v184, v184
	v_rcp_f32_e32 v185, v185
	v_rcp_f32_e32 v186, v186
	v_rcp_f32_e32 v187, v187
	v_rcp_f32_e32 v188, v188
	v_rcp_f32_e32 v189, v189
	v_rcp_f32_e32 v190, v190
	v_rcp_f32_e32 v191, v191
	v_mul_f32_e32 v184, v4, v184
	v_mul_f32_e32 v185, v5, v185
	v_mul_f32_e32 v186, v6, v186
	v_mul_f32_e32 v187, v7, v187
	v_mul_f32_e32 v188, v0, v188
	v_mul_f32_e32 v189, v1, v189
	v_mul_f32_e32 v190, v2, v190
	v_mul_f32_e32 v191, v3, v191
	v_mul_f32_e32 v184, v12, v184
	v_mul_f32_e32 v185, v13, v185
	v_mul_f32_e32 v186, v14, v186
	v_mul_f32_e32 v187, v15, v187
	v_mul_f32_e32 v188, v8, v188
	v_mul_f32_e32 v189, v9, v189
	v_mul_f32_e32 v190, v10, v190
	v_mul_f32_e32 v191, v11, v191
	v_cvt_pk_bf16_f32 v196, v184, v185
	v_cvt_pk_bf16_f32 v197, v186, v187
	v_cvt_pk_bf16_f32 v198, v188, v189
	v_cvt_pk_bf16_f32 v199, v190, v191
	v_add_u32_e32 v201, 0xf2000, v248
	global_store_dwordx4 v201, v[196:199], s[48:49] sc0 sc1

; __device__ __forceinline__ float rs_from(const float* p, int n4, float inv_n) {
;     float s = 0.f;
;     for (int i = 0; i < n4; ++i) { const f32x4 v = *(const f32x4*)(p + 4 * i); s += (v[0] + v[1]) + (v[2] + v[3]); }
;     return rsqrtf(s * inv_n + EPS);
;     __device__ __forceinline__ void operator()(AccRef acc, const pg8::Unit& u, int wr, int wc, int fr, int fq) const {
;         const int row0 = u.pm * 256 + wr * 64 + fr, col0 = u.pn * 128 + wc * 32 + 8 * fq;
; #pragma unroll
;         for (int ai = 0; ai < 2; ++ai)
; #pragma unroll
;             for (int m = 0; m < 4; ++m) {
;                 const int row = row0 + ai * 128 + m * 16;
;                 const float rs = rs_from(ssp + (size_t)row * 16, 4, 1.0f / 1024.0f);
;                 f32x4 o[2];
; #pragma unroll
;                 for (int n = 0; n < 2; ++n)
; #pragma unroll
;                     for (int j = 0; j < 4; ++j) {
;                         const float g = acc[ai][0][m][n][j] * rs, up = acc[ai][1][m][n][j] * rs;
;                         o[n][j] = g * __builtin_amdgcn_rcpf(1.0f + __expf(-g)) * up;
;                     }
;                 *(u32x4*)(act + (size_t)row * FF + col0) = pack8(o[0], o[1]);
.LBB0_2484:
.Lswi_beg3:
	v_add_u32_e32 v249, 0x2000, v247
	global_load_dwordx4 v[154:157], v249, s[46:47]
	global_load_dwordx4 v[158:161], v249, s[46:47] offset:1024
	global_load_dwordx4 v[162:165], v249, s[46:47] offset:2048
	global_load_dwordx4 v[166:169], v249, s[46:47] offset:3072
	v_mbcnt_lo_u32_b32 v170, -1, 0
	v_mbcnt_hi_u32_b32 v170, -1, v170
	v_xor_b32_e32 v171, 16, v170
	v_xor_b32_e32 v172, 32, v170
	v_lshlrev_b32_e32 v171, 2, v171
	v_lshlrev_b32_e32 v172, 2, v172
	v_lshl_or_b32 v173, s59, 7, v148
	v_lshlrev_b32_e32 v173, 1, v173
	v_mad_u32_u24 v248, v246, s51, v173
	s_waitcnt vmcnt(12)
	v_add_f32_e32 v230, v230, v231
	v_add_f32_e32 v232, v232, v233
	v_add_f32_e32 v234, v234, v235
	v_add_f32_e32 v236, v236, v237
	v_add_f32_e32 v238, v238, v239
	v_add_f32_e32 v240, v240, v241
	v_add_f32_e32 v242, v242, v243
	v_add_f32_e32 v244, v244, v245
	v_add_f32_e32 v230, v230, v232
	v_add_f32_e32 v234, v234, v236
	v_add_f32_e32 v238, v238, v240
	v_add_f32_e32 v242, v242, v244
	ds_bpermute_b32 v231, v171, v230
	ds_bpermute_b32 v235, v171, v234
	ds_bpermute_b32 v239, v171, v238
	ds_bpermute_b32 v243, v171, v242
	s_waitcnt lgkmcnt(0)
	v_add_f32_e32 v230, v230, v231
	v_add_f32_e32 v234, v234, v235
	v_add_f32_e32 v238, v238, v239
	v_add_f32_e32 v242, v242, v243
	ds_bpermute_b32 v231, v172, v230
	ds_bpermute_b32 v235, v172, v234
	ds_bpermute_b32 v239, v172, v238
	ds_bpermute_b32 v243, v172, v242
	s_waitcnt lgkmcnt(0)
	v_add_f32_e32 v230, v230, v231
	v_add_f32_e32 v234, v234, v235
	v_add_f32_e32 v238, v238, v239
	v_add_f32_e32 v242, v242, v243
	v_fmamk_f32 v230, v230, 0x3a800000, v152
	v_fmamk_f32 v234, v234, 0x3a800000, v152
	v_fmamk_f32 v238, v238, 0x3a800000, v152
	v_fmamk_f32 v242, v242, 0x3a800000, v152
	v_rsq_f32_e32 v230, v230
	v_rsq_f32_e32 v234, v234
	v_rsq_f32_e32 v238, v238
	v_rsq_f32_e32 v242, v242
	s_nop 0
	v_pk_mul_f32 v[116:117], v[116:117], v[230:231] op_sel_hi:[1,0]
	v_pk_mul_f32 v[118:119], v[118:119], v[230:231] op_sel_hi:[1,0]
	v_pk_mul_f32 v[112:113], v[112:113], v[230:231] op_sel_hi:[1,0]
	v_pk_mul_f32 v[114:115], v[114:115], v[230:231] op_sel_hi:[1,0]
	v_pk_mul_f32 v[124:125], v[124:125], v[230:231] op_sel_hi:[1,0]
	v_pk_mul_f32 v[126:127], v[126:127], v[230:231] op_sel_hi:[1,0]
	v_pk_mul_f32 v[120:121], v[120:121], v[230:231] op_sel_hi:[1,0]
	v_pk_mul_f32 v[122:123], v[122:123], v[230:231] op_sel_hi:[1,0]
	v_mul_f32_e32 v176, 0xbfb8aa3b, v116
	v_mul_f32_e32 v177, 0xbfb8aa3b, v117
	v_mul_f32_e32 v178, 0xbfb8aa3b, v118
	v_mul_f32_e32 v179, 0xbfb8aa3b, v119
	v_mul_f32_e32 v180, 0xbfb8aa3b, v112
	v_mul_f32_e32 v181, 0xbfb8aa3b, v113
	v_mul_f32_e32 v182, 0xbfb8aa3b, v114
	v_mul_f32_e32 v183, 0xbfb8aa3b, v115
	v_exp_f32_e32 v176, v176
	v_exp_f32_e32 v177, v177
	v_exp_f32_e32 v178, v178
	v_exp_f32_e32 v179, v179
	v_exp_f32_e32 v180, v180
	v_exp_f32_e32 v181, v181
	v_exp_f32_e32 v182, v182
	v_exp_f32_e32 v183, v183
	v_add_f32_e32 v176, 1.0, v176
	v_add_f32_e32 v177, 1.0, v177
	v_add_f32_e32 v178, 1.0, v178
	v_add_f32_e32 v179, 1.0, v179
	v_add_f32_e32 v180, 1.0, v180
	v_add_f32_e32 v181, 1.0, v181
	v_add_f32_e32 v182, 1.0, v182
	v_add_f32_e32 v183, 1.0, v183
	v_rcp_f32_e32 v176, v176
	v_rcp_f32_e32 v177, v177
	v_rcp_f32_e32 v178, v178
	v_rcp_f32_e32 v179, v179
	v_rcp_f32_e32 v180, v180
	v_rcp_f32_e32 v181, v181
	v_rcp_f32_e32 v182, v182
	v_rcp_f32_e32 v183, v183
	v_mul_f32_e32 v176, v116, v176
	v_mul_f32_e32 v177, v117, v177
	v_mul_f32_e32 v178, v118, v178
	v_mul_f32_e32 v179, v119, v179
	v_mul_f32_e32 v180, v112, v180
	v_mul_f32_e32 v181, v113, v181
	v_mul_f32_e32 v182, v114, v182
	v_mul_f32_e32 v183, v115, v183
	v_mul_f32_e32 v176, v124, v176
	v_mul_f32_e32 v177, v125, v177
	v_mul_f32_e32 v178, v126, v178
	v_mul_f32_e32 v179, v127, v179
	v_mul_f32_e32 v180, v120, v180
	v_mul_f32_e32 v181, v121, v181
	v_mul_f32_e32 v182, v122, v182
	v_mul_f32_e32 v183, v123, v183
	v_cvt_pk_bf16_f32 v192, v176, v177
	v_cvt_pk_bf16_f32 v193, v178, v179
	v_cvt_pk_bf16_f32 v194, v180, v181
	v_cvt_pk_bf16_f32 v195, v182, v183
	v_mov_b32_e32 v200, v248
	global_store_dwordx4 v200, v[192:195], s[48:49] sc0 sc1
	v_pk_mul_f32 v[100:101], v[100:101], v[234:235] op_sel_hi:[1,0]
	v_pk_mul_f32 v[102:103], v[102:103], v[234:235] op_sel_hi:[1,0]
	v_pk_mul_f32 v[96:97], v[96:97], v[234:235] op_sel_hi:[1,0]
	v_pk_mul_f32 v[98:99], v[98:99], v[234:235] op_sel_hi:[1,0]
	v_pk_mul_f32 v[108:109], v[108:109], v[234:235] op_sel_hi:[1,0]
	v_pk_mul_f32 v[110:111], v[110:111], v[234:235] op_sel_hi:[1,0]
	v_pk_mul_f32 v[104:105], v[104:105], v[234:235] op_sel_hi:[1,0]
	v_pk_mul_f32 v[106:107], v[106:107], v[234:235] op_sel_hi:[1,0]
	v_mul_f32_e32 v184, 0xbfb8aa3b, v100
	v_mul_f32_e32 v185, 0xbfb8aa3b, v101
	v_mul_f32_e32 v186, 0xbfb8aa3b, v102
	v_mul_f32_e32 v187, 0xbfb8aa3b, v103
	v_mul_f32_e32 v188, 0xbfb8aa3b, v96
	v_mul_f32_e32 v189, 0xbfb8aa3b, v97
	v_mul_f32_e32 v190, 0xbfb8aa3b, v98
	v_mul_f32_e32 v191, 0xbfb8aa3b, v99
	v_exp_f32_e32 v184, v184
	v_exp_f32_e32 v185, v185
	v_exp_f32_e32 v186, v186
	v_exp_f32_e32 v187, v187
	v_exp_f32_e32 v188, v188
	v_exp_f32_e32 v189, v189
	v_exp_f32_e32 v190, v190
	v_exp_f32_e32 v191, v191
	v_add_f32_e32 v184, 1.0, v184
	v_add_f32_e32 v185, 1.0, v185
	v_add_f32_e32 v186, 1.0, v186
	v_add_f32_e32 v187, 1.0, v187
	v_add_f32_e32 v188, 1.0, v188
	v_add_f32_e32 v189, 1.0, v189
	v_add_f32_e32 v190, 1.0, v190
	v_add_f32_e32 v191, 1.0, v191
	v_rcp_f32_e32 v184, v184
	v_rcp_f32_e32 v185, v185
	v_rcp_f32_e32 v186, v186
	v_rcp_f32_e32 v187, v187
	v_rcp_f32_e32 v188, v188
	v_rcp_f32_e32 v189, v189
	v_rcp_f32_e32 v190, v190
	v_rcp_f32_e32 v191, v191
	v_mul_f32_e32 v184, v100, v184
	v_mul_f32_e32 v185, v101, v185
	v_mul_f32_e32 v186, v102, v186
; __device__ __forceinline__ float rs_from(const float* p, int n4, float inv_n) {
;     float s = 0.f;
;     for (int i = 0; i < n4; ++i) { const f32x4 v = *(const f32x4*)(p + 4 * i); s += (v[0] + v[1]) + (v[2] + v[3]); }
;     return rsqrtf(s * inv_n + EPS);
;     __device__ __forceinline__ void operator()(AccRef acc, const pg8::Unit& u, int wr, int wc, int fr, int fq) const {
;     ...
;             for (int m = 0; m < 4; ++m) {
;                 const int row = row0 + ai * 128 + m * 16;
;                 const float rs = rs_from(ssp + (size_t)row * 16, 4, 1.0f / 1024.0f);
;                 f32x4 o[2];
; #pragma unroll
;                 for (int n = 0; n < 2; ++n)
; #pragma unroll
;                     for (int j = 0; j < 4; ++j) {
;                         const float g = acc[ai][0][m][n][j] * rs, up = acc[ai][1][m][n][j] * rs;
;                         o[n][j] = g * __builtin_amdgcn_rcpf(1.0f + __expf(-g)) * up;
;                     }
;                 *(u32x4*)(act + (size_t)row * FF + col0) = pack8(o[0], o[1]);
	v_mul_f32_e32 v187, v103, v187
	v_mul_f32_e32 v188, v96, v188
	v_mul_f32_e32 v189, v97, v189
	v_mul_f32_e32 v190, v98, v190
	v_mul_f32_e32 v191, v99, v191
	v_mul_f32_e32 v184, v108, v184
	v_mul_f32_e32 v185, v109, v185
	v_mul_f32_e32 v186, v110, v186
	v_mul_f32_e32 v187, v111, v187
	v_mul_f32_e32 v188, v104, v188
	v_mul_f32_e32 v189, v105, v189
	v_mul_f32_e32 v190, v106, v190
	v_mul_f32_e32 v191, v107, v191
	v_cvt_pk_bf16_f32 v196, v184, v185
	v_cvt_pk_bf16_f32 v197, v186, v187
	v_cvt_pk_bf16_f32 v198, v188, v189
	v_cvt_pk_bf16_f32 v199, v190, v191
	v_add_u32_e32 v201, 0x16000, v248
	global_store_dwordx4 v201, v[196:199], s[48:49] sc0 sc1
	v_pk_mul_f32 v[84:85], v[84:85], v[238:239] op_sel_hi:[1,0]
	v_pk_mul_f32 v[86:87], v[86:87], v[238:239] op_sel_hi:[1,0]
	v_pk_mul_f32 v[80:81], v[80:81], v[238:239] op_sel_hi:[1,0]
	v_pk_mul_f32 v[82:83], v[82:83], v[238:239] op_sel_hi:[1,0]
	v_pk_mul_f32 v[92:93], v[92:93], v[238:239] op_sel_hi:[1,0]
	v_pk_mul_f32 v[94:95], v[94:95], v[238:239] op_sel_hi:[1,0]
	v_pk_mul_f32 v[88:89], v[88:89], v[238:239] op_sel_hi:[1,0]
	v_pk_mul_f32 v[90:91], v[90:91], v[238:239] op_sel_hi:[1,0]
	v_mul_f32_e32 v176, 0xbfb8aa3b, v84
	v_mul_f32_e32 v177, 0xbfb8aa3b, v85
	v_mul_f32_e32 v178, 0xbfb8aa3b, v86
	v_mul_f32_e32 v179, 0xbfb8aa3b, v87
	v_mul_f32_e32 v180, 0xbfb8aa3b, v80
	v_mul_f32_e32 v181, 0xbfb8aa3b, v81
	v_mul_f32_e32 v182, 0xbfb8aa3b, v82
	v_mul_f32_e32 v183, 0xbfb8aa3b, v83
	v_exp_f32_e32 v176, v176
	v_exp_f32_e32 v177, v177
	v_exp_f32_e32 v178, v178
	v_exp_f32_e32 v179, v179
	v_exp_f32_e32 v180, v180
	v_exp_f32_e32 v181, v181
	v_exp_f32_e32 v182, v182
	v_exp_f32_e32 v183, v183
	v_add_f32_e32 v176, 1.0, v176
	v_add_f32_e32 v177, 1.0, v177
	v_add_f32_e32 v178, 1.0, v178
	v_add_f32_e32 v179, 1.0, v179
	v_add_f32_e32 v180, 1.0, v180
	v_add_f32_e32 v181, 1.0, v181
	v_add_f32_e32 v182, 1.0, v182
	v_add_f32_e32 v183, 1.0, v183
	v_rcp_f32_e32 v176, v176
	v_rcp_f32_e32 v177, v177
	v_rcp_f32_e32 v178, v178
	v_rcp_f32_e32 v179, v179
	v_rcp_f32_e32 v180, v180
	v_rcp_f32_e32 v181, v181
	v_rcp_f32_e32 v182, v182
	v_rcp_f32_e32 v183, v183
	v_mul_f32_e32 v176, v84, v176
	v_mul_f32_e32 v177, v85, v177
	v_mul_f32_e32 v178, v86, v178
	v_mul_f32_e32 v179, v87, v179
	v_mul_f32_e32 v180, v80, v180
	v_mul_f32_e32 v181, v81, v181
	v_mul_f32_e32 v182, v82, v182
	v_mul_f32_e32 v183, v83, v183
	v_mul_f32_e32 v176, v92, v176
	v_mul_f32_e32 v177, v93, v177
	v_mul_f32_e32 v178, v94, v178
	v_mul_f32_e32 v179, v95, v179
	v_mul_f32_e32 v180, v88, v180
	v_mul_f32_e32 v181, v89, v181
	v_mul_f32_e32 v182, v90, v182
	v_mul_f32_e32 v183, v91, v183
	v_cvt_pk_bf16_f32 v192, v176, v177
	v_cvt_pk_bf16_f32 v193, v178, v179
	v_cvt_pk_bf16_f32 v194, v180, v181
	v_cvt_pk_bf16_f32 v195, v182, v183
	v_add_u32_e32 v200, 0x2c000, v248
	global_store_dwordx4 v200, v[192:195], s[48:49] sc0 sc1
	v_pk_mul_f32 v[68:69], v[68:69], v[242:243] op_sel_hi:[1,0]
	v_pk_mul_f32 v[70:71], v[70:71], v[242:243] op_sel_hi:[1,0]
	v_pk_mul_f32 v[64:65], v[64:65], v[242:243] op_sel_hi:[1,0]
	v_pk_mul_f32 v[66:67], v[66:67], v[242:243] op_sel_hi:[1,0]
	v_pk_mul_f32 v[76:77], v[76:77], v[242:243] op_sel_hi:[1,0]
	v_pk_mul_f32 v[78:79], v[78:79], v[242:243] op_sel_hi:[1,0]
	v_pk_mul_f32 v[72:73], v[72:73], v[242:243] op_sel_hi:[1,0]
	v_pk_mul_f32 v[74:75], v[74:75], v[242:243] op_sel_hi:[1,0]
	v_mul_f32_e32 v184, 0xbfb8aa3b, v68
	v_mul_f32_e32 v185, 0xbfb8aa3b, v69
	v_mul_f32_e32 v186, 0xbfb8aa3b, v70
	v_mul_f32_e32 v187, 0xbfb8aa3b, v71
	v_mul_f32_e32 v188, 0xbfb8aa3b, v64
	v_mul_f32_e32 v189, 0xbfb8aa3b, v65
	v_mul_f32_e32 v190, 0xbfb8aa3b, v66
	v_mul_f32_e32 v191, 0xbfb8aa3b, v67
	v_exp_f32_e32 v184, v184
	v_exp_f32_e32 v185, v185
	v_exp_f32_e32 v186, v186
	v_exp_f32_e32 v187, v187
	v_exp_f32_e32 v188, v188
	v_exp_f32_e32 v189, v189
	v_exp_f32_e32 v190, v190
	v_exp_f32_e32 v191, v191
	v_add_f32_e32 v184, 1.0, v184
	v_add_f32_e32 v185, 1.0, v185
	v_add_f32_e32 v186, 1.0, v186
	v_add_f32_e32 v187, 1.0, v187
	v_add_f32_e32 v188, 1.0, v188
	v_add_f32_e32 v189, 1.0, v189
	v_add_f32_e32 v190, 1.0, v190
	v_add_f32_e32 v191, 1.0, v191
	v_rcp_f32_e32 v184, v184
	v_rcp_f32_e32 v185, v185
	v_rcp_f32_e32 v186, v186
	v_rcp_f32_e32 v187, v187
	v_rcp_f32_e32 v188, v188
	v_rcp_f32_e32 v189, v189
	v_rcp_f32_e32 v190, v190
	v_rcp_f32_e32 v191, v191
	v_mul_f32_e32 v184, v68, v184
	v_mul_f32_e32 v185, v69, v185
	v_mul_f32_e32 v186, v70, v186
	v_mul_f32_e32 v187, v71, v187
	v_mul_f32_e32 v188, v64, v188
	v_mul_f32_e32 v189, v65, v189
	v_mul_f32_e32 v190, v66, v190
	v_mul_f32_e32 v191, v67, v191
	v_mul_f32_e32 v184, v76, v184
	v_mul_f32_e32 v185, v77, v185
	v_mul_f32_e32 v186, v78, v186
	v_mul_f32_e32 v187, v79, v187
	v_mul_f32_e32 v188, v72, v188
	v_mul_f32_e32 v189, v73, v189
	v_mul_f32_e32 v190, v74, v190
	v_mul_f32_e32 v191, v75, v191
	v_cvt_pk_bf16_f32 v196, v184, v185
	v_cvt_pk_bf16_f32 v197, v186, v187
	v_cvt_pk_bf16_f32 v198, v188, v189
	v_cvt_pk_bf16_f32 v199, v190, v191
	v_add_u32_e32 v201, 0x42000, v248
	global_store_dwordx4 v201, v[196:199], s[48:49] sc0 sc1
	s_waitcnt vmcnt(4)
	v_add_f32_e32 v154, v154, v155
	v_add_f32_e32 v156, v156, v157
	v_add_f32_e32 v158, v158, v159
	v_add_f32_e32 v160, v160, v161
	v_add_f32_e32 v162, v162, v163
	v_add_f32_e32 v164, v164, v165
	v_add_f32_e32 v166, v166, v167
	v_add_f32_e32 v168, v168, v169
	v_add_f32_e32 v154, v154, v156
	v_add_f32_e32 v158, v158, v160
	v_add_f32_e32 v162, v162, v164
	v_add_f32_e32 v166, v166, v168
	ds_bpermute_b32 v155, v171, v154
	ds_bpermute_b32 v159, v171, v158
	ds_bpermute_b32 v163, v171, v162
	ds_bpermute_b32 v167, v171, v166
	s_waitcnt lgkmcnt(0)
; __device__ __forceinline__ float rs_from(const float* p, int n4, float inv_n) {
;     float s = 0.f;
;     for (int i = 0; i < n4; ++i) { const f32x4 v = *(const f32x4*)(p + 4 * i); s += (v[0] + v[1]) + (v[2] + v[3]); }
;     return rsqrtf(s * inv_n + EPS);
;     __device__ __forceinline__ void operator()(AccRef acc, const pg8::Unit& u, int wr, int wc, int fr, int fq) const {
;     ...
;             for (int m = 0; m < 4; ++m) {
;                 const int row = row0 + ai * 128 + m * 16;
;                 const float rs = rs_from(ssp + (size_t)row * 16, 4, 1.0f / 1024.0f);
;                 f32x4 o[2];
; #pragma unroll
;                 for (int n = 0; n < 2; ++n)
; #pragma unroll
;                     for (int j = 0; j < 4; ++j) {
;                         const float g = acc[ai][0][m][n][j] * rs, up = acc[ai][1][m][n][j] * rs;
;                         o[n][j] = g * __builtin_amdgcn_rcpf(1.0f + __expf(-g)) * up;
;                     }
;                 *(u32x4*)(act + (size_t)row * FF + col0) = pack8(o[0], o[1]);
	v_add_f32_e32 v154, v154, v155
	v_add_f32_e32 v158, v158, v159
	v_add_f32_e32 v162, v162, v163
	v_add_f32_e32 v166, v166, v167
	ds_bpermute_b32 v155, v172, v154
	ds_bpermute_b32 v159, v172, v158
	ds_bpermute_b32 v163, v172, v162
	ds_bpermute_b32 v167, v172, v166
	s_waitcnt lgkmcnt(0)
	v_add_f32_e32 v154, v154, v155
	v_add_f32_e32 v158, v158, v159
	v_add_f32_e32 v162, v162, v163
	v_add_f32_e32 v166, v166, v167
	v_fmamk_f32 v154, v154, 0x3a800000, v152
	v_fmamk_f32 v158, v158, 0x3a800000, v152
	v_fmamk_f32 v162, v162, 0x3a800000, v152
	v_fmamk_f32 v166, v166, 0x3a800000, v152
	v_rsq_f32_e32 v154, v154
	v_rsq_f32_e32 v158, v158
	v_rsq_f32_e32 v162, v162
	v_rsq_f32_e32 v166, v166
	s_nop 0
	v_pk_mul_f32 v[52:53], v[52:53], v[154:155] op_sel_hi:[1,0]
	v_pk_mul_f32 v[54:55], v[54:55], v[154:155] op_sel_hi:[1,0]
	v_pk_mul_f32 v[48:49], v[48:49], v[154:155] op_sel_hi:[1,0]
	v_pk_mul_f32 v[50:51], v[50:51], v[154:155] op_sel_hi:[1,0]
	v_pk_mul_f32 v[60:61], v[60:61], v[154:155] op_sel_hi:[1,0]
	v_pk_mul_f32 v[62:63], v[62:63], v[154:155] op_sel_hi:[1,0]
	v_pk_mul_f32 v[56:57], v[56:57], v[154:155] op_sel_hi:[1,0]
	v_pk_mul_f32 v[58:59], v[58:59], v[154:155] op_sel_hi:[1,0]
	v_mul_f32_e32 v176, 0xbfb8aa3b, v52
	v_mul_f32_e32 v177, 0xbfb8aa3b, v53
	v_mul_f32_e32 v178, 0xbfb8aa3b, v54
	v_mul_f32_e32 v179, 0xbfb8aa3b, v55
	v_mul_f32_e32 v180, 0xbfb8aa3b, v48
	v_mul_f32_e32 v181, 0xbfb8aa3b, v49
	v_mul_f32_e32 v182, 0xbfb8aa3b, v50
	v_mul_f32_e32 v183, 0xbfb8aa3b, v51
	v_exp_f32_e32 v176, v176
	v_exp_f32_e32 v177, v177
	v_exp_f32_e32 v178, v178
	v_exp_f32_e32 v179, v179
	v_exp_f32_e32 v180, v180
	v_exp_f32_e32 v181, v181
	v_exp_f32_e32 v182, v182
	v_exp_f32_e32 v183, v183
	v_add_f32_e32 v176, 1.0, v176
	v_add_f32_e32 v177, 1.0, v177
	v_add_f32_e32 v178, 1.0, v178
	v_add_f32_e32 v179, 1.0, v179
	v_add_f32_e32 v180, 1.0, v180
	v_add_f32_e32 v181, 1.0, v181
	v_add_f32_e32 v182, 1.0, v182
	v_add_f32_e32 v183, 1.0, v183
	v_rcp_f32_e32 v176, v176
	v_rcp_f32_e32 v177, v177
	v_rcp_f32_e32 v178, v178
	v_rcp_f32_e32 v179, v179
	v_rcp_f32_e32 v180, v180
	v_rcp_f32_e32 v181, v181
	v_rcp_f32_e32 v182, v182
	v_rcp_f32_e32 v183, v183
	v_mul_f32_e32 v176, v52, v176
	v_mul_f32_e32 v177, v53, v177
	v_mul_f32_e32 v178, v54, v178
	v_mul_f32_e32 v179, v55, v179
	v_mul_f32_e32 v180, v48, v180
	v_mul_f32_e32 v181, v49, v181
	v_mul_f32_e32 v182, v50, v182
	v_mul_f32_e32 v183, v51, v183
	v_mul_f32_e32 v176, v60, v176
	v_mul_f32_e32 v177, v61, v177
	v_mul_f32_e32 v178, v62, v178
	v_mul_f32_e32 v179, v63, v179
	v_mul_f32_e32 v180, v56, v180
	v_mul_f32_e32 v181, v57, v181
	v_mul_f32_e32 v182, v58, v182
	v_mul_f32_e32 v183, v59, v183
	v_cvt_pk_bf16_f32 v192, v176, v177
	v_cvt_pk_bf16_f32 v193, v178, v179
	v_cvt_pk_bf16_f32 v194, v180, v181
	v_cvt_pk_bf16_f32 v195, v182, v183
	v_add_u32_e32 v200, 0xb0000, v248
	global_store_dwordx4 v200, v[192:195], s[48:49] sc0 sc1
	v_pk_mul_f32 v[36:37], v[36:37], v[158:159] op_sel_hi:[1,0]
	v_pk_mul_f32 v[38:39], v[38:39], v[158:159] op_sel_hi:[1,0]
	v_pk_mul_f32 v[32:33], v[32:33], v[158:159] op_sel_hi:[1,0]
	v_pk_mul_f32 v[34:35], v[34:35], v[158:159] op_sel_hi:[1,0]
	v_pk_mul_f32 v[44:45], v[44:45], v[158:159] op_sel_hi:[1,0]
	v_pk_mul_f32 v[46:47], v[46:47], v[158:159] op_sel_hi:[1,0]
	v_pk_mul_f32 v[40:41], v[40:41], v[158:159] op_sel_hi:[1,0]
	v_pk_mul_f32 v[42:43], v[42:43], v[158:159] op_sel_hi:[1,0]
	v_mul_f32_e32 v184, 0xbfb8aa3b, v36
	v_mul_f32_e32 v185, 0xbfb8aa3b, v37
	v_mul_f32_e32 v186, 0xbfb8aa3b, v38
	v_mul_f32_e32 v187, 0xbfb8aa3b, v39
	v_mul_f32_e32 v188, 0xbfb8aa3b, v32
	v_mul_f32_e32 v189, 0xbfb8aa3b, v33
	v_mul_f32_e32 v190, 0xbfb8aa3b, v34
	v_mul_f32_e32 v191, 0xbfb8aa3b, v35
	v_exp_f32_e32 v184, v184
	v_exp_f32_e32 v185, v185
	v_exp_f32_e32 v186, v186
	v_exp_f32_e32 v187, v187
	v_exp_f32_e32 v188, v188
	v_exp_f32_e32 v189, v189
	v_exp_f32_e32 v190, v190
	v_exp_f32_e32 v191, v191
	v_add_f32_e32 v184, 1.0, v184
	v_add_f32_e32 v185, 1.0, v185
	v_add_f32_e32 v186, 1.0, v186
	v_add_f32_e32 v187, 1.0, v187
	v_add_f32_e32 v188, 1.0, v188
	v_add_f32_e32 v189, 1.0, v189
	v_add_f32_e32 v190, 1.0, v190
	v_add_f32_e32 v191, 1.0, v191
	v_rcp_f32_e32 v184, v184
	v_rcp_f32_e32 v185, v185
	v_rcp_f32_e32 v186, v186
	v_rcp_f32_e32 v187, v187
	v_rcp_f32_e32 v188, v188
	v_rcp_f32_e32 v189, v189
	v_rcp_f32_e32 v190, v190
	v_rcp_f32_e32 v191, v191
	v_mul_f32_e32 v184, v36, v184
	v_mul_f32_e32 v185, v37, v185
	v_mul_f32_e32 v186, v38, v186
	v_mul_f32_e32 v187, v39, v187
	v_mul_f32_e32 v188, v32, v188
	v_mul_f32_e32 v189, v33, v189
	v_mul_f32_e32 v190, v34, v190
	v_mul_f32_e32 v191, v35, v191
	v_mul_f32_e32 v184, v44, v184
	v_mul_f32_e32 v185, v45, v185
	v_mul_f32_e32 v186, v46, v186
	v_mul_f32_e32 v187, v47, v187
;     __device__ __forceinline__ void operator()(AccRef acc, const pg8::Unit& u, int wr, int wc, int fr, int fq) const {
;     ...
;             for (int m = 0; m < 4; ++m) {
;                 const int row = row0 + ai * 128 + m * 16;
;                 const float rs = rs_from(ssp + (size_t)row * 16, 4, 1.0f / 1024.0f);
;                 f32x4 o[2];
; #pragma unroll
;                 for (int n = 0; n < 2; ++n)
; #pragma unroll
;                     for (int j = 0; j < 4; ++j) {
;                         const float g = acc[ai][0][m][n][j] * rs, up = acc[ai][1][m][n][j] * rs;
;                         o[n][j] = g * __builtin_amdgcn_rcpf(1.0f + __expf(-g)) * up;
;                     }
;                 *(u32x4*)(act + (size_t)row * FF + col0) = pack8(o[0], o[1]);
	v_mul_f32_e32 v188, v40, v188
	v_mul_f32_e32 v189, v41, v189
	v_mul_f32_e32 v190, v42, v190
	v_mul_f32_e32 v191, v43, v191
	v_cvt_pk_bf16_f32 v196, v184, v185
	v_cvt_pk_bf16_f32 v197, v186, v187
	v_cvt_pk_bf16_f32 v198, v188, v189
	v_cvt_pk_bf16_f32 v199, v190, v191
	v_add_u32_e32 v201, 0xc6000, v248
	global_store_dwordx4 v201, v[196:199], s[48:49] sc0 sc1
	v_pk_mul_f32 v[20:21], v[20:21], v[162:163] op_sel_hi:[1,0]
	v_pk_mul_f32 v[22:23], v[22:23], v[162:163] op_sel_hi:[1,0]
	v_pk_mul_f32 v[16:17], v[16:17], v[162:163] op_sel_hi:[1,0]
	v_pk_mul_f32 v[18:19], v[18:19], v[162:163] op_sel_hi:[1,0]
	v_pk_mul_f32 v[28:29], v[28:29], v[162:163] op_sel_hi:[1,0]
	v_pk_mul_f32 v[30:31], v[30:31], v[162:163] op_sel_hi:[1,0]
	v_pk_mul_f32 v[24:25], v[24:25], v[162:163] op_sel_hi:[1,0]
	v_pk_mul_f32 v[26:27], v[26:27], v[162:163] op_sel_hi:[1,0]
	v_mul_f32_e32 v176, 0xbfb8aa3b, v20
	v_mul_f32_e32 v177, 0xbfb8aa3b, v21
	v_mul_f32_e32 v178, 0xbfb8aa3b, v22
	v_mul_f32_e32 v179, 0xbfb8aa3b, v23
	v_mul_f32_e32 v180, 0xbfb8aa3b, v16
	v_mul_f32_e32 v181, 0xbfb8aa3b, v17
	v_mul_f32_e32 v182, 0xbfb8aa3b, v18
	v_mul_f32_e32 v183, 0xbfb8aa3b, v19
	v_exp_f32_e32 v176, v176
	v_exp_f32_e32 v177, v177
	v_exp_f32_e32 v178, v178
	v_exp_f32_e32 v179, v179
	v_exp_f32_e32 v180, v180
	v_exp_f32_e32 v181, v181
	v_exp_f32_e32 v182, v182
	v_exp_f32_e32 v183, v183
	v_add_f32_e32 v176, 1.0, v176
	v_add_f32_e32 v177, 1.0, v177
	v_add_f32_e32 v178, 1.0, v178
	v_add_f32_e32 v179, 1.0, v179
	v_add_f32_e32 v180, 1.0, v180
	v_add_f32_e32 v181, 1.0, v181
	v_add_f32_e32 v182, 1.0, v182
	v_add_f32_e32 v183, 1.0, v183
	v_rcp_f32_e32 v176, v176
	v_rcp_f32_e32 v177, v177
	v_rcp_f32_e32 v178, v178
	v_rcp_f32_e32 v179, v179
	v_rcp_f32_e32 v180, v180
	v_rcp_f32_e32 v181, v181
	v_rcp_f32_e32 v182, v182
	v_rcp_f32_e32 v183, v183
	v_mul_f32_e32 v176, v20, v176
	v_mul_f32_e32 v177, v21, v177
	v_mul_f32_e32 v178, v22, v178
	v_mul_f32_e32 v179, v23, v179
	v_mul_f32_e32 v180, v16, v180
	v_mul_f32_e32 v181, v17, v181
	v_mul_f32_e32 v182, v18, v182
	v_mul_f32_e32 v183, v19, v183
	v_mul_f32_e32 v176, v28, v176
	v_mul_f32_e32 v177, v29, v177
	v_mul_f32_e32 v178, v30, v178
	v_mul_f32_e32 v179, v31, v179
	v_mul_f32_e32 v180, v24, v180
	v_mul_f32_e32 v181, v25, v181
	v_mul_f32_e32 v182, v26, v182
	v_mul_f32_e32 v183, v27, v183
	v_cvt_pk_bf16_f32 v192, v176, v177
	v_cvt_pk_bf16_f32 v193, v178, v179
	v_cvt_pk_bf16_f32 v194, v180, v181
	v_cvt_pk_bf16_f32 v195, v182, v183
	v_add_u32_e32 v200, 0xdc000, v248
	global_store_dwordx4 v200, v[192:195], s[48:49] sc0 sc1
	v_pk_mul_f32 v[4:5], v[4:5], v[166:167] op_sel_hi:[1,0]
	v_pk_mul_f32 v[6:7], v[6:7], v[166:167] op_sel_hi:[1,0]
	v_pk_mul_f32 v[0:1], v[0:1], v[166:167] op_sel_hi:[1,0]
	v_pk_mul_f32 v[2:3], v[2:3], v[166:167] op_sel_hi:[1,0]
	v_pk_mul_f32 v[12:13], v[12:13], v[166:167] op_sel_hi:[1,0]
	v_pk_mul_f32 v[14:15], v[14:15], v[166:167] op_sel_hi:[1,0]
	v_pk_mul_f32 v[8:9], v[8:9], v[166:167] op_sel_hi:[1,0]
	v_pk_mul_f32 v[10:11], v[10:11], v[166:167] op_sel_hi:[1,0]
	v_mul_f32_e32 v184, 0xbfb8aa3b, v4
	v_mul_f32_e32 v185, 0xbfb8aa3b, v5
	v_mul_f32_e32 v186, 0xbfb8aa3b, v6
	v_mul_f32_e32 v187, 0xbfb8aa3b, v7
	v_mul_f32_e32 v188, 0xbfb8aa3b, v0
	v_mul_f32_e32 v189, 0xbfb8aa3b, v1
	v_mul_f32_e32 v190, 0xbfb8aa3b, v2
	v_mul_f32_e32 v191, 0xbfb8aa3b, v3
	v_exp_f32_e32 v184, v184
	v_exp_f32_e32 v185, v185
	v_exp_f32_e32 v186, v186
	v_exp_f32_e32 v187, v187
	v_exp_f32_e32 v188, v188
	v_exp_f32_e32 v189, v189
	v_exp_f32_e32 v190, v190
	v_exp_f32_e32 v191, v191
	v_add_f32_e32 v184, 1.0, v184
	v_add_f32_e32 v185, 1.0, v185
	v_add_f32_e32 v186, 1.0, v186
	v_add_f32_e32 v187, 1.0, v187
	v_add_f32_e32 v188, 1.0, v188
	v_add_f32_e32 v189, 1.0, v189
	v_add_f32_e32 v190, 1.0, v190
	v_add_f32_e32 v191, 1.0, v191
	v_rcp_f32_e32 v184, v184
	v_rcp_f32_e32 v185, v185
	v_rcp_f32_e32 v186, v186
	v_rcp_f32_e32 v187, v187
	v_rcp_f32_e32 v188, v188
	v_rcp_f32_e32 v189, v189
	v_rcp_f32_e32 v190, v190
	v_rcp_f32_e32 v191, v191
	v_mul_f32_e32 v184, v4, v184
	v_mul_f32_e32 v185, v5, v185
	v_mul_f32_e32 v186, v6, v186
	v_mul_f32_e32 v187, v7, v187
	v_mul_f32_e32 v188, v0, v188
	v_mul_f32_e32 v189, v1, v189
	v_mul_f32_e32 v190, v2, v190
	v_mul_f32_e32 v191, v3, v191
	v_mul_f32_e32 v184, v12, v184
	v_mul_f32_e32 v185, v13, v185
	v_mul_f32_e32 v186, v14, v186
	v_mul_f32_e32 v187, v15, v187
	v_mul_f32_e32 v188, v8, v188
	v_mul_f32_e32 v189, v9, v189
	v_mul_f32_e32 v190, v10, v190
	v_mul_f32_e32 v191, v11, v191
	v_cvt_pk_bf16_f32 v196, v184, v185
	v_cvt_pk_bf16_f32 v197, v186, v187
	v_cvt_pk_bf16_f32 v198, v188, v189
	v_cvt_pk_bf16_f32 v199, v190, v191
	v_add_u32_e32 v201, 0xf2000, v248
	global_store_dwordx4 v201, v[196:199], s[48:49] sc0 sc1
